# baseline (speedup 1.0000x reference)
; #define G_STAGE(bufoff, gbase, voff) do { _Pragma("unroll") for (int _i = 0; _i < 2; ++_i) \
;         __builtin_amdgcn_global_load_lds((const unsigned*)((const char*)(gbase) + (voff)[_i]), (LAS unsigned*)(lds + (bufoff) + ldsw + _i * 8192), 16, 0, 0); } while (0)
; #define G_LDA(dst, b, h) do { _Pragma("unroll") for (int m = 0; m < 4; ++m) _Pragma("unroll") for (int k = 0; k < 2; ++k) dst[m][k] = *(const LAS bf16x8*)(lds + G_SA(b, h) + aoff + m * 2048 + k * 1024); } while (0)
; #define G_LDB(dst, b, h) do { _Pragma("unroll") for (int n = 0; n < 2; ++n) _Pragma("unroll") for (int k = 0; k < 2; ++k) dst[n][k] = *(const LAS bf16x8*)(lds + G_SB(b, h) + boff + n * 2048 + k * 1024); } while (0)
; #define G_MMA(ai, bj, At, Bt) do { __builtin_amdgcn_s_setprio(1); _Pragma("unroll") for (int m = 0; m < 4; ++m) _Pragma("unroll") for (int n = 0; n < 2; ++n) _Pragma("unroll") for (int k = 0; k < 2; ++k) \
;         acc[ai][bj][m][n] = __builtin_amdgcn_mfma_f32_16x16x32_bf16(Bt[n][k], At[m][k], acc[ai][bj][m][n], 0, 0, 0); __builtin_amdgcn_s_setprio(0); } while (0)
; #define G_WAIT_V(n) asm volatile("s_waitcnt vmcnt(" #n ")" ::: "memory")
; #define G_WAIT_L(n) asm volatile("s_waitcnt lgkmcnt(" #n ")" ::: "memory")
; #define G_BAR __builtin_amdgcn_s_barrier()
; #define G_SCHED __builtin_amdgcn_sched_barrier(0)
; template <class J>
; DI void gemm_phase(LAS unsigned char* lds, const J& job) {
;     ...
;       const bool last = (t == nt - 2);
;       const char* a1 = cA + G_KT(t + 1);
;       const char* a2 = last ? nA + G_KT(0) : cA + G_KT(t + 2); const char* b2 = last ? nB + G_KT(0) : cB + G_KT(t + 2);
;       const char* a3 = last ? nA + G_KT(1) : cA + G_KT(t + 3); const char* b3 = last ? nB + G_KT(1) : cB + G_KT(t + 3);
;       G_LDB(B0, 0, 0); G_SCHED; G_LDA(At, 0, 0); G_STAGE(G_SA(1, 1), a1 + hstepA, voffA);
;       G_WAIT_L(8); G_BAR; G_WAIT_L(0); G_MMA(0, 0, At, B0); G_BAR; G_SCHED;
;       G_LDB(B1, 0, 1); G_STAGE(G_SB(0, 0), b2, voffB);
;       G_BAR; G_WAIT_L(0); G_MMA(0, 1, At, B1); G_BAR;
;       G_LDA(At, 0, 1); G_STAGE(G_SA(0, 0), a2, voffA);
;       G_BAR; G_WAIT_L(0); G_MMA(1, 0, At, B0); G_BAR; G_SCHED;
;       G_STAGE(G_SB(0, 1), b2 + hstepB, voffB);
;       G_WAIT_V(6); G_BAR; G_MMA(1, 1, At, B1); G_BAR;
.LBB0_42:
	s_add_i32 s1, s57, 0xffffff80
	s_and_b32 s0, s44, 0xf80
	s_and_b32 s1, s1, 0xf00
	s_add_u32 s2, s70, s1
	s_addc_u32 s72, s71, 0
	s_add_u32 s1, s68, s1
	s_addc_u32 s73, s69, 0
	s_and_b32 s74, s57, 0xf80
	s_add_u32 s80, s70, s74
	s_addc_u32 s75, s71, 0
	s_add_u32 s54, s68, s74
	s_addc_u32 s55, s69, 0
	s_cmp_eq_u32 s7, 28
	s_cselect_b32 s77, vcc_lo, s72
	s_cselect_b32 s76, s47, s2
	s_cselect_b32 s79, s33, s73
	s_cselect_b32 s78, vcc_hi, s1
	s_cselect_b32 s75, s4, s75
	s_cselect_b32 s74, s97, s80
	s_cselect_b32 s73, s6, s55
	s_cselect_b32 s72, s5, s54
	s_add_i32 s2, s84, 0x100
	v_add_u32_e32 v140, s2, v162
	ds_read_b128 v[128:131], v140
	ds_read_b128 v[132:135], v140 offset:1024
	ds_read_b128 v[136:139], v140 offset:2048
	ds_read_b128 v[140:143], v140 offset:3072
	s_add_u32 s0, s21, s0
	s_addc_u32 s1, s23, 0
	v_lshl_add_u64 v[158:159], s[0:1], 0, v[148:149]
	s_add_i32 m0, s25, 0xc000
	ds_read_b128 v[154:157], v163
	ds_read_b128 v[164:167], v163 offset:1024
	ds_read_b128 v[168:171], v163 offset:2048
	ds_read_b128 v[172:175], v163 offset:3072
	ds_read_b128 v[176:179], v163 offset:4096
	ds_read_b128 v[180:183], v163 offset:5120
	ds_read_b128 v[184:187], v163 offset:6144
	ds_read_b128 v[188:191], v163 offset:7168
	global_load_lds_dwordx4 v[158:159], off
	s_add_i32 m0, s25, 0xe000
	v_lshl_add_u64 v[158:159], s[0:1], 0, v[150:151]
	global_load_lds_dwordx4 v[158:159], off
	s_waitcnt lgkmcnt(8)
	s_barrier
	s_waitcnt lgkmcnt(0)
	v_mfma_f32_16x16x32_bf16 v[124:127], v[128:131], v[154:157], v[124:127]
	v_mfma_f32_16x16x32_bf16 v[120:123], v[136:139], v[154:157], v[120:123]
	v_mfma_f32_16x16x32_bf16 v[108:111], v[128:131], v[168:171], v[108:111]
	v_mfma_f32_16x16x32_bf16 v[104:107], v[136:139], v[168:171], v[104:107]
	v_mfma_f32_16x16x32_bf16 v[92:95], v[128:131], v[176:179], v[92:95]
	v_mfma_f32_16x16x32_bf16 v[88:91], v[136:139], v[176:179], v[88:91]
	v_mfma_f32_16x16x32_bf16 v[76:79], v[128:131], v[184:187], v[76:79]
	v_mfma_f32_16x16x32_bf16 v[72:75], v[136:139], v[184:187], v[72:75]
	v_mfma_f32_16x16x32_bf16 v[124:127], v[132:135], v[164:167], v[124:127]
	v_mfma_f32_16x16x32_bf16 v[120:123], v[140:143], v[164:167], v[120:123]
	v_mfma_f32_16x16x32_bf16 v[108:111], v[132:135], v[172:175], v[108:111]
	v_mfma_f32_16x16x32_bf16 v[104:107], v[140:143], v[172:175], v[104:107]
	v_mfma_f32_16x16x32_bf16 v[92:95], v[132:135], v[180:183], v[92:95]
	v_mfma_f32_16x16x32_bf16 v[88:91], v[140:143], v[180:183], v[88:91]
	v_mfma_f32_16x16x32_bf16 v[76:79], v[132:135], v[188:191], v[76:79]
	v_mfma_f32_16x16x32_bf16 v[72:75], v[140:143], v[188:191], v[72:75]
	s_barrier
	s_add_i32 s54, s85, 0x100
	v_add_u32_e32 v158, s54, v162
	s_add_i32 s0, s2, s14
	ds_read_b128 v[192:195], v158
	ds_read_b128 v[196:199], v158 offset:1024
	ds_read_b128 v[200:203], v158 offset:2048
	ds_read_b128 v[204:207], v158 offset:3072
	s_mov_b32 m0, s0
	v_lshl_add_u64 v[158:159], s[78:79], 0, v[146:147]
	global_load_lds_dwordx4 v[158:159], off
	s_add_i32 m0, s0, 0x2000
	v_lshl_add_u64 v[158:159], s[78:79], 0, v[152:153]
	global_load_lds_dwordx4 v[158:159], off
	s_barrier
	s_waitcnt lgkmcnt(0)
	v_mfma_f32_16x16x32_bf16 v[116:119], v[192:195], v[154:157], v[116:119]
	v_mfma_f32_16x16x32_bf16 v[112:115], v[200:203], v[154:157], v[112:115]
	v_mfma_f32_16x16x32_bf16 v[100:103], v[192:195], v[168:171], v[100:103]
	v_mfma_f32_16x16x32_bf16 v[96:99], v[200:203], v[168:171], v[96:99]
	v_mfma_f32_16x16x32_bf16 v[84:87], v[192:195], v[176:179], v[84:87]
	v_mfma_f32_16x16x32_bf16 v[80:83], v[200:203], v[176:179], v[80:83]
	v_mfma_f32_16x16x32_bf16 v[68:71], v[192:195], v[184:187], v[68:71]
	v_mfma_f32_16x16x32_bf16 v[64:67], v[200:203], v[184:187], v[64:67]
	v_mfma_f32_16x16x32_bf16 v[116:119], v[196:199], v[164:167], v[116:119]
	v_mfma_f32_16x16x32_bf16 v[112:115], v[204:207], v[164:167], v[112:115]
	v_mfma_f32_16x16x32_bf16 v[100:103], v[196:199], v[172:175], v[100:103]
	v_mfma_f32_16x16x32_bf16 v[96:99], v[204:207], v[172:175], v[96:99]
	v_mfma_f32_16x16x32_bf16 v[84:87], v[196:199], v[180:183], v[84:87]
	v_mfma_f32_16x16x32_bf16 v[80:83], v[204:207], v[180:183], v[80:83]
	v_mfma_f32_16x16x32_bf16 v[68:71], v[196:199], v[188:191], v[68:71]
	v_mfma_f32_16x16x32_bf16 v[64:67], v[204:207], v[188:191], v[64:67]
	s_mov_b32 m0, s25
	v_lshl_add_u64 v[158:159], s[76:77], 0, v[148:149]
	s_barrier
	ds_read_b128 v[154:157], v163 offset:16384
	ds_read_b128 v[164:167], v163 offset:17408
	ds_read_b128 v[168:171], v163 offset:18432
	ds_read_b128 v[172:175], v163 offset:19456
	ds_read_b128 v[176:179], v163 offset:20480
	ds_read_b128 v[180:183], v163 offset:21504
	ds_read_b128 v[184:187], v163 offset:22528
	ds_read_b128 v[188:191], v163 offset:23552
	global_load_lds_dwordx4 v[158:159], off
	s_mov_b32 m0, s36
	v_lshl_add_u64 v[158:159], s[76:77], 0, v[150:151]
	global_load_lds_dwordx4 v[158:159], off
	s_barrier
	s_waitcnt lgkmcnt(0)
	v_mfma_f32_16x16x32_bf16 v[60:63], v[128:131], v[154:157], v[60:63]
	v_mfma_f32_16x16x32_bf16 v[56:59], v[136:139], v[154:157], v[56:59]
	v_mfma_f32_16x16x32_bf16 v[44:47], v[128:131], v[168:171], v[44:47]
	v_mfma_f32_16x16x32_bf16 v[40:43], v[136:139], v[168:171], v[40:43]
	v_mfma_f32_16x16x32_bf16 v[28:31], v[128:131], v[176:179], v[28:31]
	v_mfma_f32_16x16x32_bf16 v[24:27], v[136:139], v[176:179], v[24:27]
	v_mfma_f32_16x16x32_bf16 v[20:23], v[128:131], v[184:187], v[20:23]
	v_mfma_f32_16x16x32_bf16 v[12:15], v[136:139], v[184:187], v[12:15]
	v_mfma_f32_16x16x32_bf16 v[60:63], v[132:135], v[164:167], v[60:63]
	v_mfma_f32_16x16x32_bf16 v[56:59], v[140:143], v[164:167], v[56:59]
	v_mfma_f32_16x16x32_bf16 v[44:47], v[132:135], v[172:175], v[44:47]
	v_mfma_f32_16x16x32_bf16 v[40:43], v[140:143], v[172:175], v[40:43]
	v_mfma_f32_16x16x32_bf16 v[28:31], v[132:135], v[180:183], v[28:31]
	v_mfma_f32_16x16x32_bf16 v[24:27], v[140:143], v[180:183], v[24:27]
	v_mfma_f32_16x16x32_bf16 v[20:23], v[132:135], v[188:191], v[20:23]
	v_mfma_f32_16x16x32_bf16 v[12:15], v[140:143], v[188:191], v[12:15]
	s_barrier
; #define G_STAGE(bufoff, gbase, voff) do { _Pragma("unroll") for (int _i = 0; _i < 2; ++_i) \
;         __builtin_amdgcn_global_load_lds((const unsigned*)((const char*)(gbase) + (voff)[_i]), (LAS unsigned*)(lds + (bufoff) + ldsw + _i * 8192), 16, 0, 0); } while (0)
; #define G_LDA(dst, b, h) do { _Pragma("unroll") for (int m = 0; m < 4; ++m) _Pragma("unroll") for (int k = 0; k < 2; ++k) dst[m][k] = *(const LAS bf16x8*)(lds + G_SA(b, h) + aoff + m * 2048 + k * 1024); } while (0)
; #define G_LDB(dst, b, h) do { _Pragma("unroll") for (int n = 0; n < 2; ++n) _Pragma("unroll") for (int k = 0; k < 2; ++k) dst[n][k] = *(const LAS bf16x8*)(lds + G_SB(b, h) + boff + n * 2048 + k * 1024); } while (0)
; #define G_MMA(ai, bj, At, Bt) do { __builtin_amdgcn_s_setprio(1); _Pragma("unroll") for (int m = 0; m < 4; ++m) _Pragma("unroll") for (int n = 0; n < 2; ++n) _Pragma("unroll") for (int k = 0; k < 2; ++k) \
;         acc[ai][bj][m][n] = __builtin_amdgcn_mfma_f32_16x16x32_bf16(Bt[n][k], At[m][k], acc[ai][bj][m][n], 0, 0, 0); __builtin_amdgcn_s_setprio(0); } while (0)
; #define G_WAIT_V(n) asm volatile("s_waitcnt vmcnt(" #n ")" ::: "memory")
; #define G_WAIT_L(n) asm volatile("s_waitcnt lgkmcnt(" #n ")" ::: "memory")
; #define G_BAR __builtin_amdgcn_s_barrier()
; #define G_SCHED __builtin_amdgcn_sched_barrier(0)
; template <class J>
; DI void gemm_phase(LAS unsigned char* lds, const J& job) {
;     ...
;       G_STAGE(G_SB(0, 1), b2 + hstepB, voffB);
;       G_WAIT_V(6); G_BAR; G_MMA(1, 1, At, B1); G_BAR;
;       G_LDB(B0, 1, 0); G_SCHED; G_LDA(At, 1, 0); G_STAGE(G_SA(0, 1), a2 + hstepA, voffA);
;       G_WAIT_L(8); G_BAR; G_WAIT_L(0); G_MMA(0, 0, At, B0); G_BAR; G_SCHED;
;       G_LDB(B1, 1, 1); G_STAGE(G_SB(1, 0), b3, voffB);
;       G_BAR; G_WAIT_L(0); G_MMA(0, 1, At, B1); G_BAR;
;       G_LDA(At, 1, 1); G_STAGE(G_SA(1, 0), a3, voffA);
;       G_BAR; G_WAIT_L(0); G_MMA(1, 0, At, B0); G_BAR; G_SCHED;
	s_add_u32 s0, s78, 0x80000
	s_addc_u32 s1, s79, 0
	s_add_i32 s2, s54, s14
	s_mov_b32 m0, s2
	v_lshl_add_u64 v[128:129], s[0:1], 0, v[146:147]
	global_load_lds_dwordx4 v[128:129], off
	s_add_i32 m0, s2, 0x2000
	v_lshl_add_u64 v[128:129], s[0:1], 0, v[152:153]
	global_load_lds_dwordx4 v[128:129], off
	s_waitcnt vmcnt(6)
	s_barrier
	v_mfma_f32_16x16x32_bf16 v[52:55], v[192:195], v[154:157], v[52:55]
	v_mfma_f32_16x16x32_bf16 v[48:51], v[200:203], v[154:157], v[48:51]
	v_mfma_f32_16x16x32_bf16 v[36:39], v[192:195], v[168:171], v[36:39]
	v_mfma_f32_16x16x32_bf16 v[32:35], v[200:203], v[168:171], v[32:35]
	v_mfma_f32_16x16x32_bf16 v[16:19], v[192:195], v[176:179], v[16:19]
	v_mfma_f32_16x16x32_bf16 v[8:11], v[200:203], v[176:179], v[8:11]
	v_mfma_f32_16x16x32_bf16 v[4:7], v[192:195], v[184:187], v[4:7]
	v_mfma_f32_16x16x32_bf16 v[0:3], v[200:203], v[184:187], v[0:3]
	v_mfma_f32_16x16x32_bf16 v[52:55], v[196:199], v[164:167], v[52:55]
	v_mfma_f32_16x16x32_bf16 v[48:51], v[204:207], v[164:167], v[48:51]
	v_mfma_f32_16x16x32_bf16 v[36:39], v[196:199], v[172:175], v[36:39]
	v_mfma_f32_16x16x32_bf16 v[32:35], v[204:207], v[172:175], v[32:35]
	v_mfma_f32_16x16x32_bf16 v[16:19], v[196:199], v[180:183], v[16:19]
	v_mfma_f32_16x16x32_bf16 v[8:11], v[204:207], v[180:183], v[8:11]
	v_mfma_f32_16x16x32_bf16 v[4:7], v[196:199], v[188:191], v[4:7]
	v_mfma_f32_16x16x32_bf16 v[0:3], v[204:207], v[188:191], v[0:3]
	s_add_i32 s2, s88, 0x100
	v_add_u32_e32 v140, s2, v162
	s_barrier
	ds_read_b128 v[128:131], v140
	ds_read_b128 v[132:135], v140 offset:1024
	ds_read_b128 v[136:139], v140 offset:2048
	ds_read_b128 v[140:143], v140 offset:3072
	s_add_u32 s0, s76, 0x80000
	s_addc_u32 s1, s77, 0
	s_mov_b32 m0, s37
	v_lshl_add_u64 v[158:159], s[0:1], 0, v[148:149]
	ds_read_b128 v[154:157], v163 offset:32768
	ds_read_b128 v[164:167], v163 offset:33792
	ds_read_b128 v[168:171], v163 offset:34816
	ds_read_b128 v[172:175], v163 offset:35840
	ds_read_b128 v[176:179], v163 offset:36864
	ds_read_b128 v[180:183], v163 offset:37888
	ds_read_b128 v[184:187], v163 offset:38912
	ds_read_b128 v[188:191], v163 offset:39936
	global_load_lds_dwordx4 v[158:159], off
	s_mov_b32 m0, s38
	v_lshl_add_u64 v[158:159], s[0:1], 0, v[150:151]
	global_load_lds_dwordx4 v[158:159], off
	s_waitcnt lgkmcnt(8)
	s_barrier
	s_waitcnt lgkmcnt(0)
	v_mfma_f32_16x16x32_bf16 v[124:127], v[128:131], v[154:157], v[124:127]
	v_mfma_f32_16x16x32_bf16 v[120:123], v[136:139], v[154:157], v[120:123]
	v_mfma_f32_16x16x32_bf16 v[108:111], v[128:131], v[168:171], v[108:111]
	v_mfma_f32_16x16x32_bf16 v[104:107], v[136:139], v[168:171], v[104:107]
	v_mfma_f32_16x16x32_bf16 v[92:95], v[128:131], v[176:179], v[92:95]
	v_mfma_f32_16x16x32_bf16 v[88:91], v[136:139], v[176:179], v[88:91]
	v_mfma_f32_16x16x32_bf16 v[76:79], v[128:131], v[184:187], v[76:79]
	v_mfma_f32_16x16x32_bf16 v[72:75], v[136:139], v[184:187], v[72:75]
	v_mfma_f32_16x16x32_bf16 v[124:127], v[132:135], v[164:167], v[124:127]
	v_mfma_f32_16x16x32_bf16 v[120:123], v[140:143], v[164:167], v[120:123]
	v_mfma_f32_16x16x32_bf16 v[108:111], v[132:135], v[172:175], v[108:111]
	v_mfma_f32_16x16x32_bf16 v[104:107], v[140:143], v[172:175], v[104:107]
	v_mfma_f32_16x16x32_bf16 v[92:95], v[132:135], v[180:183], v[92:95]
	v_mfma_f32_16x16x32_bf16 v[88:91], v[140:143], v[180:183], v[88:91]
	v_mfma_f32_16x16x32_bf16 v[76:79], v[132:135], v[188:191], v[76:79]
	v_mfma_f32_16x16x32_bf16 v[72:75], v[140:143], v[188:191], v[72:75]
	s_barrier
	s_add_i32 s54, s89, 0x100
	v_add_u32_e32 v158, s54, v162
	s_add_i32 s0, s2, s14
	ds_read_b128 v[192:195], v158
	ds_read_b128 v[196:199], v158 offset:1024
	ds_read_b128 v[200:203], v158 offset:2048
	ds_read_b128 v[204:207], v158 offset:3072
	s_mov_b32 m0, s0
	v_lshl_add_u64 v[158:159], s[72:73], 0, v[146:147]
	global_load_lds_dwordx4 v[158:159], off
	s_add_i32 m0, s0, 0x2000
	v_lshl_add_u64 v[158:159], s[72:73], 0, v[152:153]
	global_load_lds_dwordx4 v[158:159], off
	s_barrier
	s_waitcnt lgkmcnt(0)
	v_mfma_f32_16x16x32_bf16 v[116:119], v[192:195], v[154:157], v[116:119]
	v_mfma_f32_16x16x32_bf16 v[112:115], v[200:203], v[154:157], v[112:115]
	v_mfma_f32_16x16x32_bf16 v[100:103], v[192:195], v[168:171], v[100:103]
	v_mfma_f32_16x16x32_bf16 v[96:99], v[200:203], v[168:171], v[96:99]
	v_mfma_f32_16x16x32_bf16 v[84:87], v[192:195], v[176:179], v[84:87]
	v_mfma_f32_16x16x32_bf16 v[80:83], v[200:203], v[176:179], v[80:83]
	v_mfma_f32_16x16x32_bf16 v[68:71], v[192:195], v[184:187], v[68:71]
	v_mfma_f32_16x16x32_bf16 v[64:67], v[200:203], v[184:187], v[64:67]
	v_mfma_f32_16x16x32_bf16 v[116:119], v[196:199], v[164:167], v[116:119]
	v_mfma_f32_16x16x32_bf16 v[112:115], v[204:207], v[164:167], v[112:115]
	v_mfma_f32_16x16x32_bf16 v[100:103], v[196:199], v[172:175], v[100:103]
	v_mfma_f32_16x16x32_bf16 v[96:99], v[204:207], v[172:175], v[96:99]
	v_mfma_f32_16x16x32_bf16 v[84:87], v[196:199], v[180:183], v[84:87]
	v_mfma_f32_16x16x32_bf16 v[80:83], v[204:207], v[180:183], v[80:83]
	v_mfma_f32_16x16x32_bf16 v[68:71], v[196:199], v[188:191], v[68:71]
	v_mfma_f32_16x16x32_bf16 v[64:67], v[204:207], v[188:191], v[64:67]
	s_mov_b32 m0, s87
	v_lshl_add_u64 v[158:159], s[74:75], 0, v[148:149]
	s_barrier
; #define G_STAGE(bufoff, gbase, voff) do { _Pragma("unroll") for (int _i = 0; _i < 2; ++_i) \
;         __builtin_amdgcn_global_load_lds((const unsigned*)((const char*)(gbase) + (voff)[_i]), (LAS unsigned*)(lds + (bufoff) + ldsw + _i * 8192), 16, 0, 0); } while (0)
; #define G_MMA(ai, bj, At, Bt) do { __builtin_amdgcn_s_setprio(1); _Pragma("unroll") for (int m = 0; m < 4; ++m) _Pragma("unroll") for (int n = 0; n < 2; ++n) _Pragma("unroll") for (int k = 0; k < 2; ++k) \
;         acc[ai][bj][m][n] = __builtin_amdgcn_mfma_f32_16x16x32_bf16(Bt[n][k], At[m][k], acc[ai][bj][m][n], 0, 0, 0); __builtin_amdgcn_s_setprio(0); } while (0)
; #define G_WAIT_V(n) asm volatile("s_waitcnt vmcnt(" #n ")" ::: "memory")
; #define G_WAIT_L(n) asm volatile("s_waitcnt lgkmcnt(" #n ")" ::: "memory")
; #define G_BAR __builtin_amdgcn_s_barrier()
; #define G_SCHED __builtin_amdgcn_sched_barrier(0)
; template <class J>
; DI void gemm_phase(LAS unsigned char* lds, const J& job) {
;     ...
;       G_BAR; G_WAIT_L(0); G_MMA(1, 0, At, B0); G_BAR; G_SCHED;
;       G_STAGE(G_SB(1, 1), b3 + hstepB, voffB);
;       G_WAIT_V(6); G_BAR; G_MMA(1, 1, At, B1); G_BAR;
;   DI void epi(const Acc& acc, const Unit& u, int wr, int wc, int fr, int fq) const {
;     ...
;     for (int ai = 0; ai < 2; ++ai) {
;       f32x4 res[4][2][2];
; #pragma unroll
;       for (int m = 0; m < 4; ++m) {
;         const int row = u.pm * 256 + ai * HALF + wr * 64 + m * 16 + fr;
;         const float* src = (l == 0) ? xp + (size_t)row * DM : out + (size_t)row * DM;
; #pragma unroll
;         for (int bj = 0; bj < 2; ++bj) { const int col = u.pn * 256 + bj * HALF + wc * 32 + 8 * fq; res[m][bj][0] = *(const f32x4*)(src + col); res[m][bj][1] = *(const f32x4*)(src + col + 4); }
;       }
	ds_read_b128 v[154:157], v163 offset:49152
	ds_read_b128 v[164:167], v163 offset:50176
	ds_read_b128 v[168:171], v163 offset:51200
	ds_read_b128 v[172:175], v163 offset:52224
	ds_read_b128 v[176:179], v163 offset:53248
	ds_read_b128 v[180:183], v163 offset:54272
	ds_read_b128 v[184:187], v163 offset:55296
	ds_read_b128 v[188:191], v163 offset:56320
	global_load_lds_dwordx4 v[158:159], off
	s_mov_b32 m0, s94
	v_lshl_add_u64 v[158:159], s[74:75], 0, v[150:151]
	global_load_lds_dwordx4 v[158:159], off
	s_barrier
	s_waitcnt lgkmcnt(0)
	v_mfma_f32_16x16x32_bf16 v[60:63], v[128:131], v[154:157], v[60:63]
	v_mfma_f32_16x16x32_bf16 v[56:59], v[136:139], v[154:157], v[56:59]
	v_mfma_f32_16x16x32_bf16 v[44:47], v[128:131], v[168:171], v[44:47]
	v_mfma_f32_16x16x32_bf16 v[40:43], v[136:139], v[168:171], v[40:43]
	v_mfma_f32_16x16x32_bf16 v[28:31], v[128:131], v[176:179], v[28:31]
	v_mfma_f32_16x16x32_bf16 v[24:27], v[136:139], v[176:179], v[24:27]
	v_mfma_f32_16x16x32_bf16 v[20:23], v[128:131], v[184:187], v[20:23]
	v_mfma_f32_16x16x32_bf16 v[12:15], v[136:139], v[184:187], v[12:15]
	v_mfma_f32_16x16x32_bf16 v[60:63], v[132:135], v[164:167], v[60:63]
	v_mfma_f32_16x16x32_bf16 v[56:59], v[140:143], v[164:167], v[56:59]
	v_mfma_f32_16x16x32_bf16 v[44:47], v[132:135], v[172:175], v[44:47]
	v_mfma_f32_16x16x32_bf16 v[40:43], v[140:143], v[172:175], v[40:43]
	v_mfma_f32_16x16x32_bf16 v[28:31], v[132:135], v[180:183], v[28:31]
	v_mfma_f32_16x16x32_bf16 v[24:27], v[140:143], v[180:183], v[24:27]
	v_mfma_f32_16x16x32_bf16 v[20:23], v[132:135], v[188:191], v[20:23]
	v_mfma_f32_16x16x32_bf16 v[12:15], v[140:143], v[188:191], v[12:15]
	s_barrier
	s_add_u32 s0, s72, 0x80000
	s_addc_u32 s1, s73, 0
	s_add_i32 s2, s54, s14
	s_mov_b32 m0, s2
	v_lshl_add_u64 v[128:129], s[0:1], 0, v[146:147]
	global_load_lds_dwordx4 v[128:129], off
	s_add_i32 m0, s2, 0x2000
	v_lshl_add_u64 v[128:129], s[0:1], 0, v[152:153]
	global_load_lds_dwordx4 v[128:129], off
	s_waitcnt vmcnt(6)
	s_barrier
	v_mfma_f32_16x16x32_bf16 v[52:55], v[192:195], v[154:157], v[52:55]
	v_mfma_f32_16x16x32_bf16 v[48:51], v[200:203], v[154:157], v[48:51]
	v_mfma_f32_16x16x32_bf16 v[36:39], v[192:195], v[168:171], v[36:39]
	v_mfma_f32_16x16x32_bf16 v[32:35], v[200:203], v[168:171], v[32:35]
	v_mfma_f32_16x16x32_bf16 v[16:19], v[192:195], v[176:179], v[16:19]
	v_mfma_f32_16x16x32_bf16 v[8:11], v[200:203], v[176:179], v[8:11]
	v_mfma_f32_16x16x32_bf16 v[4:7], v[192:195], v[184:187], v[4:7]
	v_mfma_f32_16x16x32_bf16 v[0:3], v[200:203], v[184:187], v[0:3]
	v_mfma_f32_16x16x32_bf16 v[52:55], v[196:199], v[164:167], v[52:55]
	v_mfma_f32_16x16x32_bf16 v[48:51], v[204:207], v[164:167], v[48:51]
	v_mfma_f32_16x16x32_bf16 v[36:39], v[196:199], v[172:175], v[36:39]
	v_mfma_f32_16x16x32_bf16 v[32:35], v[204:207], v[172:175], v[32:35]
	v_mfma_f32_16x16x32_bf16 v[16:19], v[196:199], v[180:183], v[16:19]
	v_mfma_f32_16x16x32_bf16 v[8:11], v[204:207], v[180:183], v[8:11]
	v_mfma_f32_16x16x32_bf16 v[4:7], v[196:199], v[188:191], v[4:7]
	v_mfma_f32_16x16x32_bf16 v[0:3], v[204:207], v[188:191], v[0:3]
	s_add_i32 s7, s7, 2
	s_addk_i32 s57, 0x100
	s_addk_i32 s44, 0x100
	s_cmp_gt_u32 s7, 29
	s_barrier
	s_cbranch_scc0 .LBB0_42
	s_lshl_b32 s0, s66, 8
	v_mov_b32_e32 v128, v161
	v_mov_b32_e32 v129, v160
	s_add_i32 s0, s0, s67
	s_and_b64 vcc, exec, s[18:19]
	v_add_u32_e32 v156, s0, v129
	s_lshl_b32 s0, s46, 8
	s_or_b32 s0, s0, s83
	v_lshl_add_u32 v128, v128, 3, s0
	v_ashrrev_i32_e32 v157, 31, v156
	v_ashrrev_i32_e32 v129, 31, v128
	v_lshlrev_b64 v[212:213], 13, v[156:157]
	v_lshl_add_u64 v[130:131], s[8:9], 0, v[212:213]
	v_lshlrev_b64 v[154:155], 2, v[128:129]
	v_lshl_add_u64 v[128:129], v[130:131], 0, v[154:155]
	global_load_dwordx4 v[164:167], v[128:129], off offset:16
	global_load_dwordx4 v[168:171], v[128:129], off
	global_load_dwordx4 v[172:175], v[128:129], off offset:528
	global_load_dwordx4 v[176:179], v[128:129], off offset:512
	v_add_u32_e32 v128, 16, v156
	v_ashrrev_i32_e32 v129, 31, v128
	v_lshlrev_b64 v[214:215], 13, v[128:129]
	v_lshl_add_u64 v[128:129], s[8:9], 0, v[214:215]
	v_lshl_add_u64 v[128:129], v[128:129], 0, v[154:155]
	global_load_dwordx4 v[180:183], v[128:129], off offset:16
	global_load_dwordx4 v[184:187], v[128:129], off
	global_load_dwordx4 v[188:191], v[128:129], off offset:528
	global_load_dwordx4 v[192:195], v[128:129], off offset:512
	v_add_u32_e32 v128, 32, v156
	v_ashrrev_i32_e32 v129, 31, v128
	v_lshlrev_b64 v[216:217], 13, v[128:129]
	v_lshl_add_u64 v[128:129], s[8:9], 0, v[216:217]
	v_lshl_add_u64 v[128:129], v[128:129], 0, v[154:155]
	global_load_dwordx4 v[196:199], v[128:129], off offset:16
	global_load_dwordx4 v[200:203], v[128:129], off
	global_load_dwordx4 v[204:207], v[128:129], off offset:528
	global_load_dwordx4 v[208:211], v[128:129], off offset:512
	v_add_u32_e32 v128, 48, v156
	v_ashrrev_i32_e32 v129, 31, v128
	v_lshlrev_b64 v[158:159], 13, v[128:129]
	v_lshl_add_u64 v[128:129], s[8:9], 0, v[158:159]
	v_lshl_add_u64 v[136:137], v[128:129], 0, v[154:155]
	global_load_dwordx4 v[132:135], v[136:137], off offset:16
	global_load_dwordx4 v[140:143], v[136:137], off
	global_load_dwordx4 v[128:131], v[136:137], off offset:528
	s_nop 0
	global_load_dwordx4 v[136:139], v[136:137], off offset:512
	v_lshl_add_u64 v[212:213], s[16:17], 0, v[212:213]
	s_mov_b32 s46, s22
	s_mov_b32 s66, s20
	s_mov_b64 s[68:69], s[64:65]
	s_mov_b64 s[70:71], s[62:63]
	s_movk_i32 s54, 0x4000
	s_movk_i32 s55, 0x6000
	v_readlane_b32 s0, v255, 23
	s_cmpk_gt_u32 s0, 0xff
	s_cbranch_scc1 .Lds_out_x
	s_barrier

; #define G_STAGE(bufoff, gbase, voff) do { _Pragma("unroll") for (int _i = 0; _i < 2; ++_i) \
;         __builtin_amdgcn_global_load_lds((const unsigned*)((const char*)(gbase) + (voff)[_i]), (LAS unsigned*)(lds + (bufoff) + ldsw + _i * 8192), 16, 0, 0); } while (0)
; #define G_LDA(dst, b, h) do { _Pragma("unroll") for (int m = 0; m < 4; ++m) _Pragma("unroll") for (int k = 0; k < 2; ++k) dst[m][k] = *(const LAS bf16x8*)(lds + G_SA(b, h) + aoff + m * 2048 + k * 1024); } while (0)
; #define G_LDB(dst, b, h) do { _Pragma("unroll") for (int n = 0; n < 2; ++n) _Pragma("unroll") for (int k = 0; k < 2; ++k) dst[n][k] = *(const LAS bf16x8*)(lds + G_SB(b, h) + boff + n * 2048 + k * 1024); } while (0)
; #define G_MMA(ai, bj, At, Bt) do { __builtin_amdgcn_s_setprio(1); _Pragma("unroll") for (int m = 0; m < 4; ++m) _Pragma("unroll") for (int n = 0; n < 2; ++n) _Pragma("unroll") for (int k = 0; k < 2; ++k) \
;         acc[ai][bj][m][n] = __builtin_amdgcn_mfma_f32_16x16x32_bf16(Bt[n][k], At[m][k], acc[ai][bj][m][n], 0, 0, 0); __builtin_amdgcn_s_setprio(0); } while (0)
; #define G_WAIT_V(n) asm volatile("s_waitcnt vmcnt(" #n ")" ::: "memory")
; #define G_WAIT_L(n) asm volatile("s_waitcnt lgkmcnt(" #n ")" ::: "memory")
; #define G_BAR __builtin_amdgcn_s_barrier()
; #define G_SCHED __builtin_amdgcn_sched_barrier(0)
; template <class J>
; DI void gemm_phase(LAS unsigned char* lds, const J& job) {
;     ...
;       const bool last = (t == nt - 2);
;       const char* a1 = cA + G_KT(t + 1);
;       const char* a2 = last ? nA + G_KT(0) : cA + G_KT(t + 2); const char* b2 = last ? nB + G_KT(0) : cB + G_KT(t + 2);
;       const char* a3 = last ? nA + G_KT(1) : cA + G_KT(t + 3); const char* b3 = last ? nB + G_KT(1) : cB + G_KT(t + 3);
;       G_LDB(B0, 0, 0); G_SCHED; G_LDA(At, 0, 0); G_STAGE(G_SA(1, 1), a1 + hstepA, voffA);
;       G_WAIT_L(8); G_BAR; G_WAIT_L(0); G_MMA(0, 0, At, B0); G_BAR; G_SCHED;
;       G_LDB(B1, 0, 1); G_STAGE(G_SB(0, 0), b2, voffB);
;       G_BAR; G_WAIT_L(0); G_MMA(0, 1, At, B1); G_BAR;
;       G_LDA(At, 0, 1); G_STAGE(G_SA(0, 0), a2, voffA);
;       G_BAR; G_WAIT_L(0); G_MMA(1, 0, At, B0); G_BAR; G_SCHED;
;       G_STAGE(G_SB(0, 1), b2 + hstepB, voffB);
;       G_WAIT_V(6); G_BAR; G_MMA(1, 1, At, B1); G_BAR;
.LBB0_74:
	s_add_i32 s1, s56, 0xffffff80
	s_and_b32 s0, s7, 0xf80
	s_and_b32 s1, s1, 0xf00
	s_add_u32 s57, s68, s1
	s_addc_u32 s70, s69, 0
	s_add_u32 s1, s66, s1
	s_addc_u32 s71, s67, 0
	s_and_b32 s72, s56, 0xf80
	s_add_u32 s80, s68, s72
	s_addc_u32 s73, s69, 0
	s_add_u32 s38, s66, s72
	s_addc_u32 s2, s67, 0
	s_cmp_eq_u32 s6, 28
	s_cselect_b32 s75, s46, s70
	s_cselect_b32 s74, s45, s57
	s_cselect_b32 s77, vcc_lo, s71
	s_cselect_b32 s76, s47, s1
	s_cselect_b32 s73, s97, s73
	s_cselect_b32 s72, s33, s80
	s_cselect_b32 s71, s5, s2
	s_cselect_b32 s70, vcc_hi, s38
	s_add_i32 s2, s84, 0x100
	v_add_u32_e32 v100, s2, v248
	ds_read_b128 v[84:87], v100
	ds_read_b128 v[88:91], v100 offset:1024
	ds_read_b128 v[96:99], v100 offset:2048
	ds_read_b128 v[100:103], v100 offset:3072
	s_add_u32 s0, s19, s0
	s_addc_u32 s1, s21, 0
	v_lshl_add_u64 v[186:187], s[0:1], 0, v[148:149]
	s_add_i32 m0, s14, 0xc000
	ds_read_b128 v[154:157], v249
	ds_read_b128 v[158:161], v249 offset:1024
	ds_read_b128 v[162:165], v249 offset:2048
	ds_read_b128 v[166:169], v249 offset:3072
	ds_read_b128 v[170:173], v249 offset:4096
	ds_read_b128 v[174:177], v249 offset:5120
	ds_read_b128 v[178:181], v249 offset:6144
	ds_read_b128 v[182:185], v249 offset:7168
	global_load_lds_dwordx4 v[186:187], off
	s_add_i32 m0, s14, 0xe000
	v_lshl_add_u64 v[186:187], s[0:1], 0, v[150:151]
	global_load_lds_dwordx4 v[186:187], off
	s_waitcnt lgkmcnt(8)
	s_barrier
	s_waitcnt lgkmcnt(0)
	v_mfma_f32_16x16x32_bf16 v[140:143], v[84:87], v[154:157], v[140:143]
	v_mfma_f32_16x16x32_bf16 v[136:139], v[96:99], v[154:157], v[136:139]
	v_mfma_f32_16x16x32_bf16 v[124:127], v[84:87], v[162:165], v[124:127]
	v_mfma_f32_16x16x32_bf16 v[120:123], v[96:99], v[162:165], v[120:123]
	v_mfma_f32_16x16x32_bf16 v[108:111], v[84:87], v[170:173], v[108:111]
	v_mfma_f32_16x16x32_bf16 v[104:107], v[96:99], v[170:173], v[104:107]
	v_mfma_f32_16x16x32_bf16 v[76:79], v[84:87], v[178:181], v[76:79]
	v_mfma_f32_16x16x32_bf16 v[72:75], v[96:99], v[178:181], v[72:75]
	v_mfma_f32_16x16x32_bf16 v[140:143], v[88:91], v[158:161], v[140:143]
	v_mfma_f32_16x16x32_bf16 v[136:139], v[100:103], v[158:161], v[136:139]
	v_mfma_f32_16x16x32_bf16 v[124:127], v[88:91], v[166:169], v[124:127]
	v_mfma_f32_16x16x32_bf16 v[120:123], v[100:103], v[166:169], v[120:123]
	v_mfma_f32_16x16x32_bf16 v[108:111], v[88:91], v[174:177], v[108:111]
	v_mfma_f32_16x16x32_bf16 v[104:107], v[100:103], v[174:177], v[104:107]
	v_mfma_f32_16x16x32_bf16 v[76:79], v[88:91], v[182:185], v[76:79]
	v_mfma_f32_16x16x32_bf16 v[72:75], v[100:103], v[182:185], v[72:75]
	s_barrier
	s_add_i32 s38, s85, 0x100
	s_add_i32 s0, s2, s78
	v_add_u32_e32 v198, s38, v248
	v_lshl_add_u64 v[202:203], s[76:77], 0, v[146:147]
	s_mov_b32 m0, s0
	ds_read_b128 v[186:189], v198
	ds_read_b128 v[190:193], v198 offset:1024
	ds_read_b128 v[194:197], v198 offset:2048
	ds_read_b128 v[198:201], v198 offset:3072
	global_load_lds_dwordx4 v[202:203], off
	s_add_i32 m0, s0, 0x2000
	v_lshl_add_u64 v[202:203], s[76:77], 0, v[152:153]
	global_load_lds_dwordx4 v[202:203], off
	s_barrier
	s_waitcnt lgkmcnt(0)
	v_mfma_f32_16x16x32_bf16 v[132:135], v[186:189], v[154:157], v[132:135]
	v_mfma_f32_16x16x32_bf16 v[128:131], v[194:197], v[154:157], v[128:131]
	v_mfma_f32_16x16x32_bf16 v[116:119], v[186:189], v[162:165], v[116:119]
	v_mfma_f32_16x16x32_bf16 v[112:115], v[194:197], v[162:165], v[112:115]
	v_mfma_f32_16x16x32_bf16 v[92:95], v[186:189], v[170:173], v[92:95]
	v_mfma_f32_16x16x32_bf16 v[80:83], v[194:197], v[170:173], v[80:83]
	v_mfma_f32_16x16x32_bf16 v[68:71], v[186:189], v[178:181], v[68:71]
	v_mfma_f32_16x16x32_bf16 v[64:67], v[194:197], v[178:181], v[64:67]
	v_mfma_f32_16x16x32_bf16 v[132:135], v[190:193], v[158:161], v[132:135]
	v_mfma_f32_16x16x32_bf16 v[128:131], v[198:201], v[158:161], v[128:131]
	v_mfma_f32_16x16x32_bf16 v[116:119], v[190:193], v[166:169], v[116:119]
	v_mfma_f32_16x16x32_bf16 v[112:115], v[198:201], v[166:169], v[112:115]
	v_mfma_f32_16x16x32_bf16 v[92:95], v[190:193], v[174:177], v[92:95]
	v_mfma_f32_16x16x32_bf16 v[80:83], v[198:201], v[174:177], v[80:83]
	v_mfma_f32_16x16x32_bf16 v[68:71], v[190:193], v[182:185], v[68:71]
	v_mfma_f32_16x16x32_bf16 v[64:67], v[198:201], v[182:185], v[64:67]
	s_mov_b32 m0, s14
	v_lshl_add_u64 v[202:203], s[74:75], 0, v[148:149]
	s_barrier
	ds_read_b128 v[154:157], v249 offset:16384
	ds_read_b128 v[158:161], v249 offset:17408
	ds_read_b128 v[162:165], v249 offset:18432
	ds_read_b128 v[166:169], v249 offset:19456
	ds_read_b128 v[170:173], v249 offset:20480
	ds_read_b128 v[174:177], v249 offset:21504
	ds_read_b128 v[178:181], v249 offset:22528
	ds_read_b128 v[182:185], v249 offset:23552
	global_load_lds_dwordx4 v[202:203], off
	s_mov_b32 m0, s15
	v_lshl_add_u64 v[202:203], s[74:75], 0, v[150:151]
	global_load_lds_dwordx4 v[202:203], off
	s_barrier
	s_waitcnt lgkmcnt(0)
	v_mfma_f32_16x16x32_bf16 v[60:63], v[84:87], v[154:157], v[60:63]
	v_mfma_f32_16x16x32_bf16 v[56:59], v[96:99], v[154:157], v[56:59]
	v_mfma_f32_16x16x32_bf16 v[44:47], v[84:87], v[162:165], v[44:47]
	v_mfma_f32_16x16x32_bf16 v[40:43], v[96:99], v[162:165], v[40:43]
	v_mfma_f32_16x16x32_bf16 v[28:31], v[84:87], v[170:173], v[28:31]
	v_mfma_f32_16x16x32_bf16 v[24:27], v[96:99], v[170:173], v[24:27]
	v_mfma_f32_16x16x32_bf16 v[12:15], v[84:87], v[178:181], v[12:15]
	v_mfma_f32_16x16x32_bf16 v[8:11], v[96:99], v[178:181], v[8:11]
	v_mfma_f32_16x16x32_bf16 v[60:63], v[88:91], v[158:161], v[60:63]
	v_mfma_f32_16x16x32_bf16 v[56:59], v[100:103], v[158:161], v[56:59]
	v_mfma_f32_16x16x32_bf16 v[44:47], v[88:91], v[166:169], v[44:47]
	v_mfma_f32_16x16x32_bf16 v[40:43], v[100:103], v[166:169], v[40:43]
	v_mfma_f32_16x16x32_bf16 v[28:31], v[88:91], v[174:177], v[28:31]
	v_mfma_f32_16x16x32_bf16 v[24:27], v[100:103], v[174:177], v[24:27]
	v_mfma_f32_16x16x32_bf16 v[12:15], v[88:91], v[182:185], v[12:15]
	v_mfma_f32_16x16x32_bf16 v[8:11], v[100:103], v[182:185], v[8:11]
	s_barrier
; #define G_STAGE(bufoff, gbase, voff) do { _Pragma("unroll") for (int _i = 0; _i < 2; ++_i) \
;         __builtin_amdgcn_global_load_lds((const unsigned*)((const char*)(gbase) + (voff)[_i]), (LAS unsigned*)(lds + (bufoff) + ldsw + _i * 8192), 16, 0, 0); } while (0)
; #define G_LDA(dst, b, h) do { _Pragma("unroll") for (int m = 0; m < 4; ++m) _Pragma("unroll") for (int k = 0; k < 2; ++k) dst[m][k] = *(const LAS bf16x8*)(lds + G_SA(b, h) + aoff + m * 2048 + k * 1024); } while (0)
; #define G_LDB(dst, b, h) do { _Pragma("unroll") for (int n = 0; n < 2; ++n) _Pragma("unroll") for (int k = 0; k < 2; ++k) dst[n][k] = *(const LAS bf16x8*)(lds + G_SB(b, h) + boff + n * 2048 + k * 1024); } while (0)
; #define G_MMA(ai, bj, At, Bt) do { __builtin_amdgcn_s_setprio(1); _Pragma("unroll") for (int m = 0; m < 4; ++m) _Pragma("unroll") for (int n = 0; n < 2; ++n) _Pragma("unroll") for (int k = 0; k < 2; ++k) \
;         acc[ai][bj][m][n] = __builtin_amdgcn_mfma_f32_16x16x32_bf16(Bt[n][k], At[m][k], acc[ai][bj][m][n], 0, 0, 0); __builtin_amdgcn_s_setprio(0); } while (0)
; #define G_WAIT_V(n) asm volatile("s_waitcnt vmcnt(" #n ")" ::: "memory")
; #define G_WAIT_L(n) asm volatile("s_waitcnt lgkmcnt(" #n ")" ::: "memory")
; #define G_BAR __builtin_amdgcn_s_barrier()
; #define G_SCHED __builtin_amdgcn_sched_barrier(0)
; template <class J>
; DI void gemm_phase(LAS unsigned char* lds, const J& job) {
;     ...
;       G_STAGE(G_SB(0, 1), b2 + hstepB, voffB);
;       G_WAIT_V(6); G_BAR; G_MMA(1, 1, At, B1); G_BAR;
;       G_LDB(B0, 1, 0); G_SCHED; G_LDA(At, 1, 0); G_STAGE(G_SA(0, 1), a2 + hstepA, voffA);
;       G_WAIT_L(8); G_BAR; G_WAIT_L(0); G_MMA(0, 0, At, B0); G_BAR; G_SCHED;
;       G_LDB(B1, 1, 1); G_STAGE(G_SB(1, 0), b3, voffB);
;       G_BAR; G_WAIT_L(0); G_MMA(0, 1, At, B1); G_BAR;
;       G_LDA(At, 1, 1); G_STAGE(G_SA(1, 0), a3, voffA);
;       G_BAR; G_WAIT_L(0); G_MMA(1, 0, At, B0); G_BAR; G_SCHED;
	s_add_u32 s0, s76, 0x1000000
	s_addc_u32 s1, s77, 0
	s_add_i32 s2, s38, s78
	s_mov_b32 m0, s2
	v_lshl_add_u64 v[84:85], s[0:1], 0, v[146:147]
	global_load_lds_dwordx4 v[84:85], off
	s_add_i32 m0, s2, 0x2000
	v_lshl_add_u64 v[84:85], s[0:1], 0, v[152:153]
	global_load_lds_dwordx4 v[84:85], off
	s_waitcnt vmcnt(6)
	s_barrier
	v_mfma_f32_16x16x32_bf16 v[52:55], v[186:189], v[154:157], v[52:55]
	v_mfma_f32_16x16x32_bf16 v[48:51], v[194:197], v[154:157], v[48:51]
	v_mfma_f32_16x16x32_bf16 v[36:39], v[186:189], v[162:165], v[36:39]
	v_mfma_f32_16x16x32_bf16 v[32:35], v[194:197], v[162:165], v[32:35]
	v_mfma_f32_16x16x32_bf16 v[20:23], v[186:189], v[170:173], v[20:23]
	v_mfma_f32_16x16x32_bf16 v[16:19], v[194:197], v[170:173], v[16:19]
	v_mfma_f32_16x16x32_bf16 v[4:7], v[186:189], v[178:181], v[4:7]
	v_mfma_f32_16x16x32_bf16 v[0:3], v[194:197], v[178:181], v[0:3]
	v_mfma_f32_16x16x32_bf16 v[52:55], v[190:193], v[158:161], v[52:55]
	v_mfma_f32_16x16x32_bf16 v[48:51], v[198:201], v[158:161], v[48:51]
	v_mfma_f32_16x16x32_bf16 v[36:39], v[190:193], v[166:169], v[36:39]
	v_mfma_f32_16x16x32_bf16 v[32:35], v[198:201], v[166:169], v[32:35]
	v_mfma_f32_16x16x32_bf16 v[20:23], v[190:193], v[174:177], v[20:23]
	v_mfma_f32_16x16x32_bf16 v[16:19], v[198:201], v[174:177], v[16:19]
	v_mfma_f32_16x16x32_bf16 v[4:7], v[190:193], v[182:185], v[4:7]
	v_mfma_f32_16x16x32_bf16 v[0:3], v[198:201], v[182:185], v[0:3]
	s_add_i32 s2, s88, 0x100
	v_add_u32_e32 v100, s2, v248
	s_barrier
	ds_read_b128 v[84:87], v100
	ds_read_b128 v[88:91], v100 offset:1024
	ds_read_b128 v[96:99], v100 offset:2048
	ds_read_b128 v[100:103], v100 offset:3072
	s_add_u32 s0, s74, 0x80000
	s_addc_u32 s1, s75, 0
	s_mov_b32 m0, s83
	v_lshl_add_u64 v[186:187], s[0:1], 0, v[148:149]
	ds_read_b128 v[154:157], v249 offset:32768
	ds_read_b128 v[158:161], v249 offset:33792
	ds_read_b128 v[162:165], v249 offset:34816
	ds_read_b128 v[166:169], v249 offset:35840
	ds_read_b128 v[170:173], v249 offset:36864
	ds_read_b128 v[174:177], v249 offset:37888
	ds_read_b128 v[178:181], v249 offset:38912
	ds_read_b128 v[182:185], v249 offset:39936
	global_load_lds_dwordx4 v[186:187], off
	s_mov_b32 m0, s36
	v_lshl_add_u64 v[186:187], s[0:1], 0, v[150:151]
	global_load_lds_dwordx4 v[186:187], off
	s_waitcnt lgkmcnt(8)
	s_barrier
	s_waitcnt lgkmcnt(0)
	v_mfma_f32_16x16x32_bf16 v[140:143], v[84:87], v[154:157], v[140:143]
	v_mfma_f32_16x16x32_bf16 v[136:139], v[96:99], v[154:157], v[136:139]
	v_mfma_f32_16x16x32_bf16 v[124:127], v[84:87], v[162:165], v[124:127]
	v_mfma_f32_16x16x32_bf16 v[120:123], v[96:99], v[162:165], v[120:123]
	v_mfma_f32_16x16x32_bf16 v[108:111], v[84:87], v[170:173], v[108:111]
	v_mfma_f32_16x16x32_bf16 v[104:107], v[96:99], v[170:173], v[104:107]
	v_mfma_f32_16x16x32_bf16 v[76:79], v[84:87], v[178:181], v[76:79]
	v_mfma_f32_16x16x32_bf16 v[72:75], v[96:99], v[178:181], v[72:75]
	v_mfma_f32_16x16x32_bf16 v[140:143], v[88:91], v[158:161], v[140:143]
	v_mfma_f32_16x16x32_bf16 v[136:139], v[100:103], v[158:161], v[136:139]
	v_mfma_f32_16x16x32_bf16 v[124:127], v[88:91], v[166:169], v[124:127]
	v_mfma_f32_16x16x32_bf16 v[120:123], v[100:103], v[166:169], v[120:123]
	v_mfma_f32_16x16x32_bf16 v[108:111], v[88:91], v[174:177], v[108:111]
	v_mfma_f32_16x16x32_bf16 v[104:107], v[100:103], v[174:177], v[104:107]
	v_mfma_f32_16x16x32_bf16 v[76:79], v[88:91], v[182:185], v[76:79]
	v_mfma_f32_16x16x32_bf16 v[72:75], v[100:103], v[182:185], v[72:75]
	s_barrier
	s_add_i32 s38, s89, 0x100
	s_add_i32 s0, s2, s78
	v_add_u32_e32 v198, s38, v248
	v_lshl_add_u64 v[202:203], s[70:71], 0, v[146:147]
	s_mov_b32 m0, s0
	ds_read_b128 v[186:189], v198
	ds_read_b128 v[190:193], v198 offset:1024
	ds_read_b128 v[194:197], v198 offset:2048
	ds_read_b128 v[198:201], v198 offset:3072
	global_load_lds_dwordx4 v[202:203], off
	s_add_i32 m0, s0, 0x2000
	v_lshl_add_u64 v[202:203], s[70:71], 0, v[152:153]
	global_load_lds_dwordx4 v[202:203], off
	s_barrier
	s_waitcnt lgkmcnt(0)
	v_mfma_f32_16x16x32_bf16 v[132:135], v[186:189], v[154:157], v[132:135]
	v_mfma_f32_16x16x32_bf16 v[128:131], v[194:197], v[154:157], v[128:131]
	v_mfma_f32_16x16x32_bf16 v[116:119], v[186:189], v[162:165], v[116:119]
	v_mfma_f32_16x16x32_bf16 v[112:115], v[194:197], v[162:165], v[112:115]
	v_mfma_f32_16x16x32_bf16 v[92:95], v[186:189], v[170:173], v[92:95]
	v_mfma_f32_16x16x32_bf16 v[80:83], v[194:197], v[170:173], v[80:83]
	v_mfma_f32_16x16x32_bf16 v[68:71], v[186:189], v[178:181], v[68:71]
	v_mfma_f32_16x16x32_bf16 v[64:67], v[194:197], v[178:181], v[64:67]
	v_mfma_f32_16x16x32_bf16 v[132:135], v[190:193], v[158:161], v[132:135]
	v_mfma_f32_16x16x32_bf16 v[128:131], v[198:201], v[158:161], v[128:131]
	v_mfma_f32_16x16x32_bf16 v[116:119], v[190:193], v[166:169], v[116:119]
	v_mfma_f32_16x16x32_bf16 v[112:115], v[198:201], v[166:169], v[112:115]
	v_mfma_f32_16x16x32_bf16 v[92:95], v[190:193], v[174:177], v[92:95]
	v_mfma_f32_16x16x32_bf16 v[80:83], v[198:201], v[174:177], v[80:83]
	v_mfma_f32_16x16x32_bf16 v[68:71], v[190:193], v[182:185], v[68:71]
	v_mfma_f32_16x16x32_bf16 v[64:67], v[198:201], v[182:185], v[64:67]
	s_mov_b32 m0, s24
	v_lshl_add_u64 v[202:203], s[72:73], 0, v[148:149]
	s_barrier
	ds_read_b128 v[154:157], v249 offset:49152
	ds_read_b128 v[158:161], v249 offset:50176
	ds_read_b128 v[162:165], v249 offset:51200
	ds_read_b128 v[166:169], v249 offset:52224
	ds_read_b128 v[170:173], v249 offset:53248
	ds_read_b128 v[174:177], v249 offset:54272
	ds_read_b128 v[178:181], v249 offset:55296
	ds_read_b128 v[182:185], v249 offset:56320
	global_load_lds_dwordx4 v[202:203], off
	s_mov_b32 m0, s25
	v_lshl_add_u64 v[202:203], s[72:73], 0, v[150:151]
	global_load_lds_dwordx4 v[202:203], off
	s_barrier
; #define G_STAGE(bufoff, gbase, voff) do { _Pragma("unroll") for (int _i = 0; _i < 2; ++_i) \
;         __builtin_amdgcn_global_load_lds((const unsigned*)((const char*)(gbase) + (voff)[_i]), (LAS unsigned*)(lds + (bufoff) + ldsw + _i * 8192), 16, 0, 0); } while (0)
; #define G_MMA(ai, bj, At, Bt) do { __builtin_amdgcn_s_setprio(1); _Pragma("unroll") for (int m = 0; m < 4; ++m) _Pragma("unroll") for (int n = 0; n < 2; ++n) _Pragma("unroll") for (int k = 0; k < 2; ++k) \
;         acc[ai][bj][m][n] = __builtin_amdgcn_mfma_f32_16x16x32_bf16(Bt[n][k], At[m][k], acc[ai][bj][m][n], 0, 0, 0); __builtin_amdgcn_s_setprio(0); } while (0)
; #define G_WAIT_V(n) asm volatile("s_waitcnt vmcnt(" #n ")" ::: "memory")
; #define G_WAIT_L(n) asm volatile("s_waitcnt lgkmcnt(" #n ")" ::: "memory")
; #define G_BAR __builtin_amdgcn_s_barrier()
; #define G_SCHED __builtin_amdgcn_sched_barrier(0)
; template <class J>
; DI void gemm_phase(LAS unsigned char* lds, const J& job) {
;     ...
;       G_BAR; G_WAIT_L(0); G_MMA(1, 0, At, B0); G_BAR; G_SCHED;
;       G_STAGE(G_SB(1, 1), b3 + hstepB, voffB);
;       G_WAIT_V(6); G_BAR; G_MMA(1, 1, At, B1); G_BAR;
	s_waitcnt lgkmcnt(0)
	v_mfma_f32_16x16x32_bf16 v[60:63], v[84:87], v[154:157], v[60:63]
	v_mfma_f32_16x16x32_bf16 v[56:59], v[96:99], v[154:157], v[56:59]
	v_mfma_f32_16x16x32_bf16 v[44:47], v[84:87], v[162:165], v[44:47]
	v_mfma_f32_16x16x32_bf16 v[40:43], v[96:99], v[162:165], v[40:43]
	v_mfma_f32_16x16x32_bf16 v[28:31], v[84:87], v[170:173], v[28:31]
	v_mfma_f32_16x16x32_bf16 v[24:27], v[96:99], v[170:173], v[24:27]
	v_mfma_f32_16x16x32_bf16 v[12:15], v[84:87], v[178:181], v[12:15]
	v_mfma_f32_16x16x32_bf16 v[8:11], v[96:99], v[178:181], v[8:11]
	v_mfma_f32_16x16x32_bf16 v[60:63], v[88:91], v[158:161], v[60:63]
	v_mfma_f32_16x16x32_bf16 v[56:59], v[100:103], v[158:161], v[56:59]
	v_mfma_f32_16x16x32_bf16 v[44:47], v[88:91], v[166:169], v[44:47]
	v_mfma_f32_16x16x32_bf16 v[40:43], v[100:103], v[166:169], v[40:43]
	v_mfma_f32_16x16x32_bf16 v[28:31], v[88:91], v[174:177], v[28:31]
	v_mfma_f32_16x16x32_bf16 v[24:27], v[100:103], v[174:177], v[24:27]
	v_mfma_f32_16x16x32_bf16 v[12:15], v[88:91], v[182:185], v[12:15]
	v_mfma_f32_16x16x32_bf16 v[8:11], v[100:103], v[182:185], v[8:11]
	s_barrier
	s_add_u32 s0, s70, 0x1000000
	s_addc_u32 s1, s71, 0
	s_add_i32 s2, s38, s78
	s_mov_b32 m0, s2
	v_lshl_add_u64 v[84:85], s[0:1], 0, v[146:147]
	global_load_lds_dwordx4 v[84:85], off
	s_add_i32 m0, s2, 0x2000
	v_lshl_add_u64 v[84:85], s[0:1], 0, v[152:153]
	global_load_lds_dwordx4 v[84:85], off
	s_waitcnt vmcnt(6)
	s_barrier
	v_mfma_f32_16x16x32_bf16 v[52:55], v[186:189], v[154:157], v[52:55]
	v_mfma_f32_16x16x32_bf16 v[48:51], v[194:197], v[154:157], v[48:51]
	v_mfma_f32_16x16x32_bf16 v[36:39], v[186:189], v[162:165], v[36:39]
	v_mfma_f32_16x16x32_bf16 v[32:35], v[194:197], v[162:165], v[32:35]
	v_mfma_f32_16x16x32_bf16 v[20:23], v[186:189], v[170:173], v[20:23]
	v_mfma_f32_16x16x32_bf16 v[16:19], v[194:197], v[170:173], v[16:19]
	v_mfma_f32_16x16x32_bf16 v[4:7], v[186:189], v[178:181], v[4:7]
	v_mfma_f32_16x16x32_bf16 v[0:3], v[194:197], v[178:181], v[0:3]
	v_mfma_f32_16x16x32_bf16 v[52:55], v[190:193], v[158:161], v[52:55]
	v_mfma_f32_16x16x32_bf16 v[48:51], v[198:201], v[158:161], v[48:51]
	v_mfma_f32_16x16x32_bf16 v[36:39], v[190:193], v[166:169], v[36:39]
	v_mfma_f32_16x16x32_bf16 v[32:35], v[198:201], v[166:169], v[32:35]
	v_mfma_f32_16x16x32_bf16 v[20:23], v[190:193], v[174:177], v[20:23]
	v_mfma_f32_16x16x32_bf16 v[16:19], v[198:201], v[174:177], v[16:19]
	v_mfma_f32_16x16x32_bf16 v[4:7], v[190:193], v[182:185], v[4:7]
	v_mfma_f32_16x16x32_bf16 v[0:3], v[198:201], v[182:185], v[0:3]
	s_add_i32 s6, s6, 2
	s_addk_i32 s56, 0x100
	s_addk_i32 s7, 0x100
	s_cmp_gt_u32 s6, 29
	s_barrier
	s_cbranch_scc0 .LBB0_74
;   DI void epi(const Acc& acc, const Unit& u, int wr, int wc, int fr, int fq) const {
;     const int cc = u.pn * 64 + 16 * wc + 4 * fq;
;     u32x2 zz[2][4][4];
; #pragma unroll
;     for (int ai = 0; ai < 2; ++ai)
; #pragma unroll
;       for (int m = 0; m < 4; ++m) {
;         const u16* zr = Z + (size_t)(u.pm * 256 + ai * HALF + wr * 64 + m * 16 + fr) * NGATE + cc;
; #pragma unroll
;         for (int br = 0; br < 4; ++br) zz[ai][m][br] = *(const u32x2*)(zr + br * 2048);
;       }
;     f32x4 bg[4];
; #pragma unroll
;     for (int br = 0; br < 4; ++br) bg[br] = *(const f32x4*)(bgate + br * 2048 + cc);
	v_mov_b32_e32 v84, v247
	v_mov_b32_e32 v85, v246
	s_lshl_b32 s0, s44, 6
	s_or_b32 s0, s0, s96
	v_lshl_add_u32 v84, v84, 2, s0
	s_lshl_b32 s0, s64, 8
	s_add_i32 s0, s0, s37
	v_add_u32_e32 v224, s0, v85
	v_ashrrev_i32_e32 v85, 31, v84
	v_lshlrev_b64 v[154:155], 1, v[84:85]
	v_ashrrev_i32_e32 v225, 31, v224
	v_lshl_add_u64 v[86:87], s[26:27], 0, v[154:155]
	v_lshlrev_b64 v[88:89], 14, v[224:225]
	v_lshl_add_u64 v[88:89], v[86:87], 0, v[88:89]
	v_add_co_u32_e32 v90, vcc, s82, v88
	v_add_u32_e32 v212, 16, v224
	s_nop 0
	v_addc_co_u32_e32 v91, vcc, 0, v89, vcc
	v_ashrrev_i32_e32 v213, 31, v212
	v_add_co_u32_e32 v96, vcc, s92, v88
	v_lshlrev_b64 v[98:99], 14, v[212:213]
	s_nop 0
	v_addc_co_u32_e32 v97, vcc, 0, v89, vcc
	v_lshl_add_u64 v[98:99], v[86:87], 0, v[98:99]
	v_add_co_u32_e32 v100, vcc, s82, v98
	v_add_u32_e32 v202, 32, v224
	s_nop 0
	v_addc_co_u32_e32 v101, vcc, 0, v99, vcc
	global_load_dwordx2 v[230:231], v[90:91], off offset:-4096
	global_load_dwordx2 v[226:227], v[90:91], off
	global_load_dwordx2 v[220:221], v[100:101], off offset:-4096
	global_load_dwordx2 v[214:215], v[100:101], off
	v_add_co_u32_e32 v90, vcc, s92, v98
	v_ashrrev_i32_e32 v203, 31, v202
	s_nop 0
	v_addc_co_u32_e32 v91, vcc, 0, v99, vcc
	global_load_dwordx2 v[232:233], v[88:89], off
	global_load_dwordx2 v[228:229], v[96:97], off
	global_load_dwordx2 v[222:223], v[98:99], off
	global_load_dwordx2 v[216:217], v[90:91], off
	v_lshlrev_b64 v[88:89], 14, v[202:203]
	v_lshl_add_u64 v[88:89], v[86:87], 0, v[88:89]
	v_add_co_u32_e32 v90, vcc, s82, v88
	v_add_u32_e32 v190, 48, v224
	s_nop 0
	v_addc_co_u32_e32 v91, vcc, 0, v89, vcc
	v_ashrrev_i32_e32 v191, 31, v190
	v_add_co_u32_e32 v96, vcc, s92, v88
	v_lshlrev_b64 v[98:99], 14, v[190:191]
	s_nop 0
	v_addc_co_u32_e32 v97, vcc, 0, v89, vcc
	v_lshl_add_u64 v[98:99], v[86:87], 0, v[98:99]
	v_add_co_u32_e32 v100, vcc, s82, v98
	v_add_u32_e32 v184, 0x80, v224
	s_nop 0
	v_addc_co_u32_e32 v101, vcc, 0, v99, vcc
	global_load_dwordx2 v[210:211], v[90:91], off offset:-4096
	global_load_dwordx2 v[206:207], v[90:91], off
	global_load_dwordx2 v[200:201], v[100:101], off offset:-4096
	global_load_dwordx2 v[192:193], v[100:101], off
	v_add_co_u32_e32 v90, vcc, s92, v98
	v_lshl_add_u64 v[84:85], v[84:85], 2, s[12:13]
	v_ashrrev_i32_e32 v185, 31, v184
	v_addc_co_u32_e32 v91, vcc, 0, v99, vcc
	global_load_dwordx4 v[100:103], v[84:85], off
	global_load_dwordx2 v[218:219], v[88:89], off
	global_load_dwordx2 v[208:209], v[96:97], off
	global_load_dwordx2 v[204:205], v[98:99], off
	global_load_dwordx2 v[198:199], v[90:91], off
	v_lshlrev_b64 v[88:89], 14, v[184:185]
	v_lshl_add_u64 v[88:89], v[86:87], 0, v[88:89]
	v_add_co_u32_e32 v90, vcc, s82, v88
	v_add_u32_e32 v174, 0x90, v224
	s_nop 0
	v_addc_co_u32_e32 v91, vcc, 0, v89, vcc
	v_add_co_u32_e32 v156, vcc, s92, v88
	v_ashrrev_i32_e32 v175, 31, v174
	s_nop 0
	v_addc_co_u32_e32 v157, vcc, 0, v89, vcc
	v_add_co_u32_e32 v96, vcc, s82, v84
	v_lshlrev_b64 v[158:159], 14, v[174:175]
	s_nop 0
	v_addc_co_u32_e32 v97, vcc, 0, v85, vcc
	global_load_dwordx4 v[96:99], v[96:97], off
	v_lshl_add_u64 v[158:159], v[86:87], 0, v[158:159]
	v_add_co_u32_e32 v160, vcc, s82, v158
	v_add_u32_e32 v164, 0xa0, v224
	s_nop 0
	v_addc_co_u32_e32 v161, vcc, 0, v159, vcc
	global_load_dwordx2 v[194:195], v[90:91], off offset:-4096
	global_load_dwordx2 v[186:187], v[90:91], off
	global_load_dwordx2 v[180:181], v[160:161], off offset:-4096
	global_load_dwordx2 v[176:177], v[160:161], off
	v_add_co_u32_e32 v90, vcc, s92, v158
	v_ashrrev_i32_e32 v165, 31, v164
	s_nop 0
	v_addc_co_u32_e32 v91, vcc, 0, v159, vcc
	global_load_dwordx2 v[196:197], v[88:89], off
	global_load_dwordx2 v[188:189], v[156:157], off
	global_load_dwordx2 v[182:183], v[158:159], off
	global_load_dwordx2 v[178:179], v[90:91], off
	v_lshlrev_b64 v[88:89], 14, v[164:165]
	v_lshl_add_u64 v[162:163], v[86:87], 0, v[88:89]
	v_add_co_u32_e32 v158, vcc, s82, v162
	v_add_u32_e32 v156, 0xb0, v224
	s_nop 0
	v_addc_co_u32_e32 v159, vcc, 0, v163, vcc
	v_add_co_u32_e32 v168, vcc, s92, v162
	v_ashrrev_i32_e32 v157, 31, v156
	s_nop 0
	v_addc_co_u32_e32 v169, vcc, 0, v163, vcc
	v_add_co_u32_e32 v88, vcc, s54, v84
	v_lshlrev_b64 v[160:161], 14, v[156:157]
	s_nop 0
	v_addc_co_u32_e32 v89, vcc, 0, v85, vcc
	global_load_dwordx4 v[88:91], v[88:89], off
	v_lshl_add_u64 v[250:251], v[86:87], 0, v[160:161]
	v_add_co_u32_e32 v86, vcc, s82, v250
	s_mov_b32 s44, s20
	s_nop 0
	v_addc_co_u32_e32 v87, vcc, 0, v251, vcc
	v_add_co_u32_e32 v84, vcc, s55, v84
	global_load_dwordx2 v[170:171], v[158:159], off offset:-4096
	global_load_dwordx2 v[166:167], v[158:159], off
	global_load_dwordx2 v[160:161], v[86:87], off offset:-4096
	s_nop 0
	global_load_dwordx2 v[158:159], v[86:87], off
	v_addc_co_u32_e32 v85, vcc, 0, v85, vcc
	global_load_dwordx4 v[84:87], v[84:85], off
	v_add_co_u32_e32 v252, vcc, s92, v250
	s_mov_b32 s64, s18
	s_nop 0
	v_addc_co_u32_e32 v253, vcc, 0, v251, vcc
	s_and_b64 vcc, exec, s[8:9]
	s_mov_b64 s[66:67], s[62:63]
	s_mov_b64 s[68:69], s[22:23]
	v_readlane_b32 s0, v255, 23
	s_cmpk_gt_u32 s0, 0xff
	s_cbranch_scc1 .Lds_gate_x
	s_barrier

; #define G_STAGE(bufoff, gbase, voff) do { _Pragma("unroll") for (int _i = 0; _i < 2; ++_i) \
;         __builtin_amdgcn_global_load_lds((const unsigned*)((const char*)(gbase) + (voff)[_i]), (LAS unsigned*)(lds + (bufoff) + ldsw + _i * 8192), 16, 0, 0); } while (0)
; #define G_LDA(dst, b, h) do { _Pragma("unroll") for (int m = 0; m < 4; ++m) _Pragma("unroll") for (int k = 0; k < 2; ++k) dst[m][k] = *(const LAS bf16x8*)(lds + G_SA(b, h) + aoff + m * 2048 + k * 1024); } while (0)
; #define G_LDB(dst, b, h) do { _Pragma("unroll") for (int n = 0; n < 2; ++n) _Pragma("unroll") for (int k = 0; k < 2; ++k) dst[n][k] = *(const LAS bf16x8*)(lds + G_SB(b, h) + boff + n * 2048 + k * 1024); } while (0)
; #define G_MMA(ai, bj, At, Bt) do { __builtin_amdgcn_s_setprio(1); _Pragma("unroll") for (int m = 0; m < 4; ++m) _Pragma("unroll") for (int n = 0; n < 2; ++n) _Pragma("unroll") for (int k = 0; k < 2; ++k) \
;         acc[ai][bj][m][n] = __builtin_amdgcn_mfma_f32_16x16x32_bf16(Bt[n][k], At[m][k], acc[ai][bj][m][n], 0, 0, 0); __builtin_amdgcn_s_setprio(0); } while (0)
; #define G_WAIT_V(n) asm volatile("s_waitcnt vmcnt(" #n ")" ::: "memory")
; #define G_WAIT_L(n) asm volatile("s_waitcnt lgkmcnt(" #n ")" ::: "memory")
; #define G_BAR __builtin_amdgcn_s_barrier()
; #define G_SCHED __builtin_amdgcn_sched_barrier(0)
; template <class J>
; DI void gemm_phase(LAS unsigned char* lds, const J& job) {
;     ...
;       const bool last = (t == nt - 2);
;       const char* a1 = cA + G_KT(t + 1);
;       const char* a2 = last ? nA + G_KT(0) : cA + G_KT(t + 2); const char* b2 = last ? nB + G_KT(0) : cB + G_KT(t + 2);
;       const char* a3 = last ? nA + G_KT(1) : cA + G_KT(t + 3); const char* b3 = last ? nB + G_KT(1) : cB + G_KT(t + 3);
;       G_LDB(B0, 0, 0); G_SCHED; G_LDA(At, 0, 0); G_STAGE(G_SA(1, 1), a1 + hstepA, voffA);
;       G_WAIT_L(8); G_BAR; G_WAIT_L(0); G_MMA(0, 0, At, B0); G_BAR; G_SCHED;
;       G_LDB(B1, 0, 1); G_STAGE(G_SB(0, 0), b2, voffB);
;       G_BAR; G_WAIT_L(0); G_MMA(0, 1, At, B1); G_BAR;
;       G_LDA(At, 0, 1); G_STAGE(G_SA(0, 0), a2, voffA);
;       G_BAR; G_WAIT_L(0); G_MMA(1, 0, At, B0); G_BAR; G_SCHED;
;       G_STAGE(G_SB(0, 1), b2 + hstepB, voffB);
;       G_WAIT_V(6); G_BAR; G_MMA(1, 1, At, B1); G_BAR;
.LBB0_104:
	s_add_i32 s1, s56, 0xffffff80
	s_and_b32 s0, s7, 0x380
	s_and_b32 s1, s1, 0x380
	s_add_u32 s57, s64, s1
	s_addc_u32 s66, s65, 0
	s_add_u32 s1, s62, s1
	s_addc_u32 s67, s63, 0
	s_and_b32 s68, s56, 0x380
	s_add_u32 s80, s64, s68
	s_addc_u32 s69, s65, 0
	s_add_u32 s97, s62, s68
	s_addc_u32 vcc_lo, s63, 0
	s_cmp_eq_u32 s6, 4
	s_cselect_b32 s71, s83, s66
	s_cselect_b32 s70, s47, s57
	s_cselect_b32 s73, s87, s67
	s_cselect_b32 s72, s86, s1
	s_cselect_b32 s69, s94, s69
	s_cselect_b32 s68, s33, s80
	s_cselect_b32 s67, s5, vcc_lo
	s_cselect_b32 s66, s96, s97
	s_add_i32 s1, s84, 0x100
	v_add_u32_e32 v134, s1, v138
	ds_read_b128 v[140:143], v134
	ds_read_b128 v[148:151], v134 offset:1024
	ds_read_b128 v[152:155], v134 offset:2048
	ds_read_b128 v[156:159], v134 offset:3072
	s_add_u32 vcc_lo, s9, s0
	s_addc_u32 vcc_hi, s17, 0
	v_lshl_add_u64 v[134:135], vcc, 0, v[132:133]
	s_add_i32 m0, s25, 0xc000
	ds_read_b128 v[160:163], v139
	ds_read_b128 v[164:167], v139 offset:1024
	ds_read_b128 v[168:171], v139 offset:2048
	ds_read_b128 v[172:175], v139 offset:3072
	ds_read_b128 v[176:179], v139 offset:4096
	ds_read_b128 v[180:183], v139 offset:5120
	ds_read_b128 v[184:187], v139 offset:6144
	ds_read_b128 v[188:191], v139 offset:7168
	global_load_lds_dwordx4 v[134:135], off
	v_lshl_add_u64 v[134:135], vcc, 0, v[130:131]
	s_add_i32 m0, s25, 0xe000
	s_nop 0
	global_load_lds_dwordx4 v[134:135], off
	s_waitcnt lgkmcnt(8)
	s_barrier
	s_waitcnt lgkmcnt(0)
	v_mfma_f32_16x16x32_bf16 v[124:127], v[140:143], v[160:163], v[124:127]
	v_mfma_f32_16x16x32_bf16 v[120:123], v[152:155], v[160:163], v[120:123]
	v_mfma_f32_16x16x32_bf16 v[116:119], v[140:143], v[168:171], v[116:119]
	v_mfma_f32_16x16x32_bf16 v[108:111], v[152:155], v[168:171], v[108:111]
	v_mfma_f32_16x16x32_bf16 v[100:103], v[140:143], v[176:179], v[100:103]
	v_mfma_f32_16x16x32_bf16 v[92:95], v[152:155], v[176:179], v[92:95]
	v_mfma_f32_16x16x32_bf16 v[84:87], v[140:143], v[184:187], v[84:87]
	v_mfma_f32_16x16x32_bf16 v[76:79], v[152:155], v[184:187], v[76:79]
	v_mfma_f32_16x16x32_bf16 v[124:127], v[148:151], v[164:167], v[124:127]
	v_mfma_f32_16x16x32_bf16 v[120:123], v[156:159], v[164:167], v[120:123]
	v_mfma_f32_16x16x32_bf16 v[116:119], v[148:151], v[172:175], v[116:119]
	v_mfma_f32_16x16x32_bf16 v[108:111], v[156:159], v[172:175], v[108:111]
	v_mfma_f32_16x16x32_bf16 v[100:103], v[148:151], v[180:183], v[100:103]
	v_mfma_f32_16x16x32_bf16 v[92:95], v[156:159], v[180:183], v[92:95]
	v_mfma_f32_16x16x32_bf16 v[84:87], v[148:151], v[188:191], v[84:87]
	v_mfma_f32_16x16x32_bf16 v[76:79], v[156:159], v[188:191], v[76:79]
	s_barrier
	s_add_i32 s0, s85, 0x100
	v_add_u32_e32 v134, s0, v138
	s_add_i32 s1, s1, s24
	ds_read_b128 v[192:195], v134
	ds_read_b128 v[196:199], v134 offset:1024
	ds_read_b128 v[200:203], v134 offset:2048
	ds_read_b128 v[204:207], v134 offset:3072
	s_mov_b32 m0, s1
	v_lshl_add_u64 v[134:135], s[72:73], 0, v[146:147]
	global_load_lds_dwordx4 v[134:135], off
	s_add_i32 m0, s1, 0x2000
	v_lshl_add_u64 v[134:135], s[72:73], 0, v[128:129]
	global_load_lds_dwordx4 v[134:135], off
	s_barrier
	s_waitcnt lgkmcnt(0)
	v_mfma_f32_16x16x32_bf16 v[112:115], v[192:195], v[160:163], v[112:115]
	v_mfma_f32_16x16x32_bf16 v[104:107], v[200:203], v[160:163], v[104:107]
	v_mfma_f32_16x16x32_bf16 v[96:99], v[192:195], v[168:171], v[96:99]
	v_mfma_f32_16x16x32_bf16 v[88:91], v[200:203], v[168:171], v[88:91]
	v_mfma_f32_16x16x32_bf16 v[80:83], v[192:195], v[176:179], v[80:83]
	v_mfma_f32_16x16x32_bf16 v[72:75], v[200:203], v[176:179], v[72:75]
	v_mfma_f32_16x16x32_bf16 v[68:71], v[192:195], v[184:187], v[68:71]
	v_mfma_f32_16x16x32_bf16 v[64:67], v[200:203], v[184:187], v[64:67]
	v_mfma_f32_16x16x32_bf16 v[112:115], v[196:199], v[164:167], v[112:115]
	v_mfma_f32_16x16x32_bf16 v[104:107], v[204:207], v[164:167], v[104:107]
	v_mfma_f32_16x16x32_bf16 v[96:99], v[196:199], v[172:175], v[96:99]
	v_mfma_f32_16x16x32_bf16 v[88:91], v[204:207], v[172:175], v[88:91]
	v_mfma_f32_16x16x32_bf16 v[80:83], v[196:199], v[180:183], v[80:83]
	v_mfma_f32_16x16x32_bf16 v[72:75], v[204:207], v[180:183], v[72:75]
	v_mfma_f32_16x16x32_bf16 v[68:71], v[196:199], v[188:191], v[68:71]
	v_mfma_f32_16x16x32_bf16 v[64:67], v[204:207], v[188:191], v[64:67]
	s_mov_b32 m0, s25
	v_lshl_add_u64 v[134:135], s[70:71], 0, v[132:133]
	s_barrier
	ds_read_b128 v[160:163], v139 offset:16384
	ds_read_b128 v[164:167], v139 offset:17408
	ds_read_b128 v[168:171], v139 offset:18432
	ds_read_b128 v[172:175], v139 offset:19456
	ds_read_b128 v[176:179], v139 offset:20480
	ds_read_b128 v[180:183], v139 offset:21504
	ds_read_b128 v[184:187], v139 offset:22528
	ds_read_b128 v[188:191], v139 offset:23552
	global_load_lds_dwordx4 v[134:135], off
	s_mov_b32 m0, s36
	v_lshl_add_u64 v[134:135], s[70:71], 0, v[130:131]
	global_load_lds_dwordx4 v[134:135], off
	s_barrier
	s_waitcnt lgkmcnt(0)
	v_mfma_f32_16x16x32_bf16 v[60:63], v[140:143], v[160:163], v[60:63]
	v_mfma_f32_16x16x32_bf16 v[56:59], v[152:155], v[160:163], v[56:59]
	v_mfma_f32_16x16x32_bf16 v[52:55], v[140:143], v[168:171], v[52:55]
	v_mfma_f32_16x16x32_bf16 v[44:47], v[152:155], v[168:171], v[44:47]
	v_mfma_f32_16x16x32_bf16 v[36:39], v[140:143], v[176:179], v[36:39]
	v_mfma_f32_16x16x32_bf16 v[28:31], v[152:155], v[176:179], v[28:31]
	v_mfma_f32_16x16x32_bf16 v[20:23], v[140:143], v[184:187], v[20:23]
	v_mfma_f32_16x16x32_bf16 v[12:15], v[152:155], v[184:187], v[12:15]
	v_mfma_f32_16x16x32_bf16 v[60:63], v[148:151], v[164:167], v[60:63]
	v_mfma_f32_16x16x32_bf16 v[56:59], v[156:159], v[164:167], v[56:59]
	v_mfma_f32_16x16x32_bf16 v[52:55], v[148:151], v[172:175], v[52:55]
	v_mfma_f32_16x16x32_bf16 v[44:47], v[156:159], v[172:175], v[44:47]
	v_mfma_f32_16x16x32_bf16 v[36:39], v[148:151], v[180:183], v[36:39]
	v_mfma_f32_16x16x32_bf16 v[28:31], v[156:159], v[180:183], v[28:31]
	v_mfma_f32_16x16x32_bf16 v[20:23], v[148:151], v[188:191], v[20:23]
	v_mfma_f32_16x16x32_bf16 v[12:15], v[156:159], v[188:191], v[12:15]
	s_barrier
; #define G_STAGE(bufoff, gbase, voff) do { _Pragma("unroll") for (int _i = 0; _i < 2; ++_i) \
;         __builtin_amdgcn_global_load_lds((const unsigned*)((const char*)(gbase) + (voff)[_i]), (LAS unsigned*)(lds + (bufoff) + ldsw + _i * 8192), 16, 0, 0); } while (0)
; #define G_LDA(dst, b, h) do { _Pragma("unroll") for (int m = 0; m < 4; ++m) _Pragma("unroll") for (int k = 0; k < 2; ++k) dst[m][k] = *(const LAS bf16x8*)(lds + G_SA(b, h) + aoff + m * 2048 + k * 1024); } while (0)
; #define G_LDB(dst, b, h) do { _Pragma("unroll") for (int n = 0; n < 2; ++n) _Pragma("unroll") for (int k = 0; k < 2; ++k) dst[n][k] = *(const LAS bf16x8*)(lds + G_SB(b, h) + boff + n * 2048 + k * 1024); } while (0)
; #define G_MMA(ai, bj, At, Bt) do { __builtin_amdgcn_s_setprio(1); _Pragma("unroll") for (int m = 0; m < 4; ++m) _Pragma("unroll") for (int n = 0; n < 2; ++n) _Pragma("unroll") for (int k = 0; k < 2; ++k) \
;         acc[ai][bj][m][n] = __builtin_amdgcn_mfma_f32_16x16x32_bf16(Bt[n][k], At[m][k], acc[ai][bj][m][n], 0, 0, 0); __builtin_amdgcn_s_setprio(0); } while (0)
; #define G_WAIT_V(n) asm volatile("s_waitcnt vmcnt(" #n ")" ::: "memory")
; #define G_WAIT_L(n) asm volatile("s_waitcnt lgkmcnt(" #n ")" ::: "memory")
; #define G_BAR __builtin_amdgcn_s_barrier()
; #define G_SCHED __builtin_amdgcn_sched_barrier(0)
; template <class J>
; DI void gemm_phase(LAS unsigned char* lds, const J& job) {
;     ...
;       G_STAGE(G_SB(0, 1), b2 + hstepB, voffB);
;       G_WAIT_V(6); G_BAR; G_MMA(1, 1, At, B1); G_BAR;
;       G_LDB(B0, 1, 0); G_SCHED; G_LDA(At, 1, 0); G_STAGE(G_SA(0, 1), a2 + hstepA, voffA);
;       G_WAIT_L(8); G_BAR; G_WAIT_L(0); G_MMA(0, 0, At, B0); G_BAR; G_SCHED;
;       G_LDB(B1, 1, 1); G_STAGE(G_SB(1, 0), b3, voffB);
;       G_BAR; G_WAIT_L(0); G_MMA(0, 1, At, B1); G_BAR;
;       G_LDA(At, 1, 1); G_STAGE(G_SA(1, 0), a3, voffA);
;       G_BAR; G_WAIT_L(0); G_MMA(1, 0, At, B0); G_BAR; G_SCHED;
	s_add_u32 s72, s72, 0x20000
	s_addc_u32 s73, s73, 0
	s_add_i32 s0, s0, s24
	s_mov_b32 m0, s0
	v_lshl_add_u64 v[134:135], s[72:73], 0, v[146:147]
	global_load_lds_dwordx4 v[134:135], off
	s_add_i32 m0, s0, 0x2000
	v_lshl_add_u64 v[134:135], s[72:73], 0, v[128:129]
	global_load_lds_dwordx4 v[134:135], off
	s_waitcnt vmcnt(6)
	s_barrier
	v_mfma_f32_16x16x32_bf16 v[48:51], v[192:195], v[160:163], v[48:51]
	v_mfma_f32_16x16x32_bf16 v[40:43], v[200:203], v[160:163], v[40:43]
	v_mfma_f32_16x16x32_bf16 v[32:35], v[192:195], v[168:171], v[32:35]
	v_mfma_f32_16x16x32_bf16 v[24:27], v[200:203], v[168:171], v[24:27]
	v_mfma_f32_16x16x32_bf16 v[16:19], v[192:195], v[176:179], v[16:19]
	v_mfma_f32_16x16x32_bf16 v[8:11], v[200:203], v[176:179], v[8:11]
	v_mfma_f32_16x16x32_bf16 v[4:7], v[192:195], v[184:187], v[4:7]
	v_mfma_f32_16x16x32_bf16 v[0:3], v[200:203], v[184:187], v[0:3]
	v_mfma_f32_16x16x32_bf16 v[48:51], v[196:199], v[164:167], v[48:51]
	v_mfma_f32_16x16x32_bf16 v[40:43], v[204:207], v[164:167], v[40:43]
	v_mfma_f32_16x16x32_bf16 v[32:35], v[196:199], v[172:175], v[32:35]
	v_mfma_f32_16x16x32_bf16 v[24:27], v[204:207], v[172:175], v[24:27]
	v_mfma_f32_16x16x32_bf16 v[16:19], v[196:199], v[180:183], v[16:19]
	v_mfma_f32_16x16x32_bf16 v[8:11], v[204:207], v[180:183], v[8:11]
	v_mfma_f32_16x16x32_bf16 v[4:7], v[196:199], v[188:191], v[4:7]
	v_mfma_f32_16x16x32_bf16 v[0:3], v[204:207], v[188:191], v[0:3]
	s_add_i32 s0, s88, 0x100
	v_add_u32_e32 v134, s0, v138
	s_barrier
	ds_read_b128 v[140:143], v134
	ds_read_b128 v[148:151], v134 offset:1024
	ds_read_b128 v[152:155], v134 offset:2048
	ds_read_b128 v[156:159], v134 offset:3072
	s_add_u32 s70, s70, 0x80000
	s_addc_u32 s71, s71, 0
	s_mov_b32 m0, s37
	v_lshl_add_u64 v[134:135], s[70:71], 0, v[132:133]
	ds_read_b128 v[160:163], v139 offset:32768
	ds_read_b128 v[164:167], v139 offset:33792
	ds_read_b128 v[168:171], v139 offset:34816
	ds_read_b128 v[172:175], v139 offset:35840
	ds_read_b128 v[176:179], v139 offset:36864
	ds_read_b128 v[180:183], v139 offset:37888
	ds_read_b128 v[184:187], v139 offset:38912
	ds_read_b128 v[188:191], v139 offset:39936
	global_load_lds_dwordx4 v[134:135], off
	s_mov_b32 m0, s38
	v_lshl_add_u64 v[134:135], s[70:71], 0, v[130:131]
	global_load_lds_dwordx4 v[134:135], off
	s_waitcnt lgkmcnt(8)
	s_barrier
	s_waitcnt lgkmcnt(0)
	v_mfma_f32_16x16x32_bf16 v[124:127], v[140:143], v[160:163], v[124:127]
	v_mfma_f32_16x16x32_bf16 v[120:123], v[152:155], v[160:163], v[120:123]
	v_mfma_f32_16x16x32_bf16 v[116:119], v[140:143], v[168:171], v[116:119]
	v_mfma_f32_16x16x32_bf16 v[108:111], v[152:155], v[168:171], v[108:111]
	v_mfma_f32_16x16x32_bf16 v[100:103], v[140:143], v[176:179], v[100:103]
	v_mfma_f32_16x16x32_bf16 v[92:95], v[152:155], v[176:179], v[92:95]
	v_mfma_f32_16x16x32_bf16 v[84:87], v[140:143], v[184:187], v[84:87]
	v_mfma_f32_16x16x32_bf16 v[76:79], v[152:155], v[184:187], v[76:79]
	v_mfma_f32_16x16x32_bf16 v[124:127], v[148:151], v[164:167], v[124:127]
	v_mfma_f32_16x16x32_bf16 v[120:123], v[156:159], v[164:167], v[120:123]
	v_mfma_f32_16x16x32_bf16 v[116:119], v[148:151], v[172:175], v[116:119]
	v_mfma_f32_16x16x32_bf16 v[108:111], v[156:159], v[172:175], v[108:111]
	v_mfma_f32_16x16x32_bf16 v[100:103], v[148:151], v[180:183], v[100:103]
	v_mfma_f32_16x16x32_bf16 v[92:95], v[156:159], v[180:183], v[92:95]
	v_mfma_f32_16x16x32_bf16 v[84:87], v[148:151], v[188:191], v[84:87]
	v_mfma_f32_16x16x32_bf16 v[76:79], v[156:159], v[188:191], v[76:79]
	s_barrier
	s_add_i32 s1, s89, 0x100
	v_add_u32_e32 v134, s1, v138
	s_add_i32 s0, s0, s24
	ds_read_b128 v[192:195], v134
	ds_read_b128 v[196:199], v134 offset:1024
	ds_read_b128 v[200:203], v134 offset:2048
	ds_read_b128 v[204:207], v134 offset:3072
	s_mov_b32 m0, s0
	v_lshl_add_u64 v[134:135], s[66:67], 0, v[146:147]
	global_load_lds_dwordx4 v[134:135], off
	s_add_i32 m0, s0, 0x2000
	v_lshl_add_u64 v[134:135], s[66:67], 0, v[128:129]
	global_load_lds_dwordx4 v[134:135], off
	s_barrier
	s_waitcnt lgkmcnt(0)
	v_mfma_f32_16x16x32_bf16 v[112:115], v[192:195], v[160:163], v[112:115]
	v_mfma_f32_16x16x32_bf16 v[104:107], v[200:203], v[160:163], v[104:107]
	v_mfma_f32_16x16x32_bf16 v[96:99], v[192:195], v[168:171], v[96:99]
	v_mfma_f32_16x16x32_bf16 v[88:91], v[200:203], v[168:171], v[88:91]
	v_mfma_f32_16x16x32_bf16 v[80:83], v[192:195], v[176:179], v[80:83]
	v_mfma_f32_16x16x32_bf16 v[72:75], v[200:203], v[176:179], v[72:75]
	v_mfma_f32_16x16x32_bf16 v[68:71], v[192:195], v[184:187], v[68:71]
	v_mfma_f32_16x16x32_bf16 v[64:67], v[200:203], v[184:187], v[64:67]
	v_mfma_f32_16x16x32_bf16 v[112:115], v[196:199], v[164:167], v[112:115]
	v_mfma_f32_16x16x32_bf16 v[104:107], v[204:207], v[164:167], v[104:107]
	v_mfma_f32_16x16x32_bf16 v[96:99], v[196:199], v[172:175], v[96:99]
	v_mfma_f32_16x16x32_bf16 v[88:91], v[204:207], v[172:175], v[88:91]
	v_mfma_f32_16x16x32_bf16 v[80:83], v[196:199], v[180:183], v[80:83]
	v_mfma_f32_16x16x32_bf16 v[72:75], v[204:207], v[180:183], v[72:75]
	v_mfma_f32_16x16x32_bf16 v[68:71], v[196:199], v[188:191], v[68:71]
	v_mfma_f32_16x16x32_bf16 v[64:67], v[204:207], v[188:191], v[64:67]
	s_mov_b32 m0, s75
	v_lshl_add_u64 v[134:135], s[68:69], 0, v[132:133]
	s_barrier
	ds_read_b128 v[160:163], v139 offset:49152
	ds_read_b128 v[164:167], v139 offset:50176
	ds_read_b128 v[168:171], v139 offset:51200
	ds_read_b128 v[172:175], v139 offset:52224
	ds_read_b128 v[176:179], v139 offset:53248
	ds_read_b128 v[180:183], v139 offset:54272
	ds_read_b128 v[184:187], v139 offset:55296
	ds_read_b128 v[188:191], v139 offset:56320
	global_load_lds_dwordx4 v[134:135], off
	s_mov_b32 m0, s76
	v_lshl_add_u64 v[134:135], s[68:69], 0, v[130:131]
	global_load_lds_dwordx4 v[134:135], off
	s_barrier
; #define G_STAGE(bufoff, gbase, voff) do { _Pragma("unroll") for (int _i = 0; _i < 2; ++_i) \
;         __builtin_amdgcn_global_load_lds((const unsigned*)((const char*)(gbase) + (voff)[_i]), (LAS unsigned*)(lds + (bufoff) + ldsw + _i * 8192), 16, 0, 0); } while (0)
; #define G_MMA(ai, bj, At, Bt) do { __builtin_amdgcn_s_setprio(1); _Pragma("unroll") for (int m = 0; m < 4; ++m) _Pragma("unroll") for (int n = 0; n < 2; ++n) _Pragma("unroll") for (int k = 0; k < 2; ++k) \
;         acc[ai][bj][m][n] = __builtin_amdgcn_mfma_f32_16x16x32_bf16(Bt[n][k], At[m][k], acc[ai][bj][m][n], 0, 0, 0); __builtin_amdgcn_s_setprio(0); } while (0)
; #define G_WAIT_V(n) asm volatile("s_waitcnt vmcnt(" #n ")" ::: "memory")
; #define G_WAIT_L(n) asm volatile("s_waitcnt lgkmcnt(" #n ")" ::: "memory")
; #define G_BAR __builtin_amdgcn_s_barrier()
; #define G_SCHED __builtin_amdgcn_sched_barrier(0)
; template <class J>
; DI void gemm_phase(LAS unsigned char* lds, const J& job) {
;     ...
;       G_BAR; G_WAIT_L(0); G_MMA(1, 0, At, B0); G_BAR; G_SCHED;
;       G_STAGE(G_SB(1, 1), b3 + hstepB, voffB);
;       G_WAIT_V(6); G_BAR; G_MMA(1, 1, At, B1); G_BAR;
	s_waitcnt lgkmcnt(0)
	v_mfma_f32_16x16x32_bf16 v[60:63], v[140:143], v[160:163], v[60:63]
	v_mfma_f32_16x16x32_bf16 v[56:59], v[152:155], v[160:163], v[56:59]
	v_mfma_f32_16x16x32_bf16 v[52:55], v[140:143], v[168:171], v[52:55]
	v_mfma_f32_16x16x32_bf16 v[44:47], v[152:155], v[168:171], v[44:47]
	v_mfma_f32_16x16x32_bf16 v[36:39], v[140:143], v[176:179], v[36:39]
	v_mfma_f32_16x16x32_bf16 v[28:31], v[152:155], v[176:179], v[28:31]
	v_mfma_f32_16x16x32_bf16 v[20:23], v[140:143], v[184:187], v[20:23]
	v_mfma_f32_16x16x32_bf16 v[12:15], v[152:155], v[184:187], v[12:15]
	v_mfma_f32_16x16x32_bf16 v[60:63], v[148:151], v[164:167], v[60:63]
	v_mfma_f32_16x16x32_bf16 v[56:59], v[156:159], v[164:167], v[56:59]
	v_mfma_f32_16x16x32_bf16 v[52:55], v[148:151], v[172:175], v[52:55]
	v_mfma_f32_16x16x32_bf16 v[44:47], v[156:159], v[172:175], v[44:47]
	v_mfma_f32_16x16x32_bf16 v[36:39], v[148:151], v[180:183], v[36:39]
	v_mfma_f32_16x16x32_bf16 v[28:31], v[156:159], v[180:183], v[28:31]
	v_mfma_f32_16x16x32_bf16 v[20:23], v[148:151], v[188:191], v[20:23]
	v_mfma_f32_16x16x32_bf16 v[12:15], v[156:159], v[188:191], v[12:15]
	s_barrier
	s_add_u32 s66, s66, 0x20000
	s_addc_u32 s67, s67, 0
	s_add_i32 s0, s1, s24
	s_mov_b32 m0, s0
	v_lshl_add_u64 v[134:135], s[66:67], 0, v[146:147]
	global_load_lds_dwordx4 v[134:135], off
	s_add_i32 m0, s0, 0x2000
	v_lshl_add_u64 v[134:135], s[66:67], 0, v[128:129]
	global_load_lds_dwordx4 v[134:135], off
	s_waitcnt vmcnt(6)
	s_barrier
	v_mfma_f32_16x16x32_bf16 v[48:51], v[192:195], v[160:163], v[48:51]
	v_mfma_f32_16x16x32_bf16 v[40:43], v[200:203], v[160:163], v[40:43]
	v_mfma_f32_16x16x32_bf16 v[32:35], v[192:195], v[168:171], v[32:35]
	v_mfma_f32_16x16x32_bf16 v[24:27], v[200:203], v[168:171], v[24:27]
	v_mfma_f32_16x16x32_bf16 v[16:19], v[192:195], v[176:179], v[16:19]
	v_mfma_f32_16x16x32_bf16 v[8:11], v[200:203], v[176:179], v[8:11]
	v_mfma_f32_16x16x32_bf16 v[4:7], v[192:195], v[184:187], v[4:7]
	v_mfma_f32_16x16x32_bf16 v[0:3], v[200:203], v[184:187], v[0:3]
	v_mfma_f32_16x16x32_bf16 v[48:51], v[196:199], v[164:167], v[48:51]
	v_mfma_f32_16x16x32_bf16 v[40:43], v[204:207], v[164:167], v[40:43]
	v_mfma_f32_16x16x32_bf16 v[32:35], v[196:199], v[172:175], v[32:35]
	v_mfma_f32_16x16x32_bf16 v[24:27], v[204:207], v[172:175], v[24:27]
	v_mfma_f32_16x16x32_bf16 v[16:19], v[196:199], v[180:183], v[16:19]
	v_mfma_f32_16x16x32_bf16 v[8:11], v[204:207], v[180:183], v[8:11]
	v_mfma_f32_16x16x32_bf16 v[4:7], v[196:199], v[188:191], v[4:7]
	v_mfma_f32_16x16x32_bf16 v[0:3], v[204:207], v[188:191], v[0:3]
	s_add_i32 s6, s6, 2
	s_addk_i32 s56, 0x100
	s_addk_i32 s7, 0x100
	s_cmp_gt_u32 s6, 5
	s_barrier
	s_cbranch_scc0 .LBB0_104
; DI unsigned pk2(float lo, float hi) { unsigned r; asm("v_cvt_pk_bf16_f32 %0, %1, %2" : "=v"(r) : "v"(lo), "v"(hi)); return r; }
; #define G_WAIT_V(n) asm volatile("s_waitcnt vmcnt(" #n ")" ::: "memory")
; #define G_BAR __builtin_amdgcn_s_barrier()
; template <class J>
; DI void gemm_phase(LAS unsigned char* lds, const J& job) {
;     ...
;     if (!has_next) break;
; #pragma unroll
;     for (int a = 0; a < 2; ++a)
; #pragma unroll
;       for (int b = 0; b < 2; ++b)
; #pragma unroll
;         for (int m = 0; m < 4; ++m)
; #pragma unroll
;           for (int n = 0; n < 2; ++n) acc[a][b][m][n] = (f32x4){0.f, 0.f, 0.f, 0.f};
;     cur = nxt; cA = nA; cB = nB; ++ui;
;   }
;   G_WAIT_V(0);
;   if (wr == 0) G_BAR;
;   DI void epi(const Acc& acc, const Unit& u, int wr, int wc, int fr, int fq) const {
;     ...
;     for (int ai = 0; ai < 2; ++ai)
; #pragma unroll
;       for (int m = 0; m < 4; ++m) {
;         const int row = u.pm * 256 + ai * HALF + wr * 64 + m * 16 + fr;
; #pragma unroll
;         for (int bj = 0; bj < 2; ++bj) {
;           const int col = u.pn * 256 + bj * HALF + wc * 32 + 8 * fq;
;           const f32x4 v0 = acc[ai][bj][m][0], v1 = acc[ai][bj][m][1];
;           u32x4 o; o.x = pk2(v0.x, v0.y); o.y = pk2(v0.z, v0.w); o.z = pk2(v1.x, v1.y); o.w = pk2(v1.z, v1.w);
;           *(u32x4*)(Z + (size_t)row * NGATE + col) = o;
;         }
	v_mov_b32_e32 v135, v137
	v_mov_b32_e32 v134, v136
	s_lshl_b32 s0, s22, 8
	s_add_i32 s0, s0, s44
	v_add_u32_e32 v134, s0, v134
	s_lshl_b32 s0, s46, 8
	s_or_b32 s0, s0, s45
	v_cvt_pk_bf16_f32 v68, v68, v69
	v_cvt_pk_bf16_f32 v69, v70, v71
	v_cvt_pk_bf16_f32 v70, v64, v65
	v_add_u32_e32 v64, 0x80, v134
	v_lshl_add_u32 v140, v135, 3, s0
	v_ashrrev_i32_e32 v135, 31, v134
	v_ashrrev_i32_e32 v65, 31, v64
	v_lshlrev_b64 v[142:143], 14, v[134:135]
	v_ashrrev_i32_e32 v141, 31, v140
	v_lshlrev_b64 v[64:65], 14, v[64:65]
	v_cvt_pk_bf16_f32 v124, v124, v125
	v_cvt_pk_bf16_f32 v125, v126, v127
	v_cvt_pk_bf16_f32 v126, v120, v121
	v_cvt_pk_bf16_f32 v127, v122, v123
	v_lshl_add_u64 v[122:123], s[26:27], 0, v[142:143]
	v_lshlrev_b64 v[120:121], 1, v[140:141]
	v_cvt_pk_bf16_f32 v112, v112, v113
	v_cvt_pk_bf16_f32 v113, v114, v115
	v_cvt_pk_bf16_f32 v114, v104, v105
	v_add_u32_e32 v104, 16, v134
	v_cvt_pk_bf16_f32 v60, v60, v61
	v_cvt_pk_bf16_f32 v61, v62, v63
	v_cvt_pk_bf16_f32 v62, v56, v57
	v_lshl_add_u64 v[56:57], s[26:27], 0, v[64:65]
	v_cvt_pk_bf16_f32 v48, v48, v49
	v_cvt_pk_bf16_f32 v49, v50, v51
	v_cvt_pk_bf16_f32 v50, v40, v41
	v_add_u32_e32 v40, 0x90, v134
	v_lshl_add_u64 v[122:123], v[122:123], 0, v[120:121]
	v_ashrrev_i32_e32 v105, 31, v104
	v_lshl_add_u64 v[56:57], v[56:57], 0, v[120:121]
	v_ashrrev_i32_e32 v41, 31, v40
	v_cvt_pk_bf16_f32 v115, v106, v107
	global_store_dwordx4 v[122:123], v[112:115], off offset:256
	v_cvt_pk_bf16_f32 v51, v42, v43
	global_store_dwordx4 v[56:57], v[48:51], off offset:256
	v_cvt_pk_bf16_f32 v106, v108, v109
	v_cvt_pk_bf16_f32 v96, v96, v97
	v_cvt_pk_bf16_f32 v97, v98, v99
	s_nop 0
	v_lshlrev_b64 v[112:113], 14, v[104:105]
	v_lshl_add_u64 v[108:109], s[26:27], 0, v[112:113]
	v_lshlrev_b64 v[48:49], 14, v[40:41]
	v_cvt_pk_bf16_f32 v98, v88, v89
	v_add_u32_e32 v88, 32, v134
	v_cvt_pk_bf16_f32 v42, v44, v45
	v_lshl_add_u64 v[44:45], s[26:27], 0, v[48:49]
	v_cvt_pk_bf16_f32 v32, v32, v33
	v_cvt_pk_bf16_f32 v33, v34, v35
	v_cvt_pk_bf16_f32 v34, v24, v25
	v_add_u32_e32 v24, 0xa0, v134
	v_lshl_add_u64 v[108:109], v[108:109], 0, v[120:121]
	v_ashrrev_i32_e32 v89, 31, v88
	v_lshl_add_u64 v[44:45], v[44:45], 0, v[120:121]
	v_ashrrev_i32_e32 v25, 31, v24
	v_cvt_pk_bf16_f32 v99, v90, v91
	global_store_dwordx4 v[108:109], v[96:99], off offset:256
	v_cvt_pk_bf16_f32 v35, v26, v27
	global_store_dwordx4 v[44:45], v[32:35], off offset:256
	v_cvt_pk_bf16_f32 v90, v92, v93
	v_cvt_pk_bf16_f32 v80, v80, v81
	v_cvt_pk_bf16_f32 v81, v82, v83
	s_nop 0
	v_lshlrev_b64 v[96:97], 14, v[88:89]
	v_lshl_add_u64 v[92:93], s[26:27], 0, v[96:97]
	v_lshlrev_b64 v[32:33], 14, v[24:25]
	v_cvt_pk_bf16_f32 v82, v72, v73
	v_add_u32_e32 v72, 48, v134
	v_cvt_pk_bf16_f32 v26, v28, v29
	v_lshl_add_u64 v[28:29], s[26:27], 0, v[32:33]
	v_cvt_pk_bf16_f32 v16, v16, v17
	v_cvt_pk_bf16_f32 v17, v18, v19
	v_cvt_pk_bf16_f32 v18, v8, v9
	v_add_u32_e32 v8, 0xb0, v134
	v_lshl_add_u64 v[92:93], v[92:93], 0, v[120:121]
	v_ashrrev_i32_e32 v73, 31, v72
	v_lshl_add_u64 v[28:29], v[28:29], 0, v[120:121]
	v_ashrrev_i32_e32 v9, 31, v8
	v_cvt_pk_bf16_f32 v83, v74, v75
	global_store_dwordx4 v[92:93], v[80:83], off offset:256
	v_cvt_pk_bf16_f32 v19, v10, v11
	global_store_dwordx4 v[28:29], v[16:19], off offset:256
	v_cvt_pk_bf16_f32 v74, v76, v77
	v_cvt_pk_bf16_f32 v10, v12, v13
	s_and_b64 vcc, exec, s[12:13]
	v_lshlrev_b64 v[80:81], 14, v[72:73]
	v_lshlrev_b64 v[16:17], 14, v[8:9]
	v_lshl_add_u64 v[76:77], s[26:27], 0, v[80:81]
	v_lshl_add_u64 v[12:13], s[26:27], 0, v[16:17]
	v_lshl_add_u64 v[76:77], v[76:77], 0, v[120:121]
	v_lshl_add_u64 v[12:13], v[12:13], 0, v[120:121]
	s_mov_b32 s46, s8
	s_mov_b32 s22, s16
	s_mov_b64 s[62:63], s[20:21]
	s_mov_b64 s[64:65], s[18:19]
	global_store_dwordx4 v[122:123], v[124:127], off
	v_cvt_pk_bf16_f32 v104, v116, v117
	v_cvt_pk_bf16_f32 v105, v118, v119
	v_cvt_pk_bf16_f32 v107, v110, v111
	global_store_dwordx4 v[108:109], v[104:107], off
	v_cvt_pk_bf16_f32 v88, v100, v101
	v_cvt_pk_bf16_f32 v89, v102, v103
	v_cvt_pk_bf16_f32 v91, v94, v95
	global_store_dwordx4 v[92:93], v[88:91], off
	v_cvt_pk_bf16_f32 v72, v84, v85
	v_cvt_pk_bf16_f32 v73, v86, v87
	v_cvt_pk_bf16_f32 v75, v78, v79
	global_store_dwordx4 v[76:77], v[72:75], off
	v_cvt_pk_bf16_f32 v71, v66, v67
	global_store_dwordx4 v[76:77], v[68:71], off offset:256
	v_cvt_pk_bf16_f32 v63, v58, v59
	global_store_dwordx4 v[56:57], v[60:63], off
	v_cvt_pk_bf16_f32 v40, v52, v53
	v_cvt_pk_bf16_f32 v41, v54, v55
	v_cvt_pk_bf16_f32 v43, v46, v47
	global_store_dwordx4 v[44:45], v[40:43], off
	v_cvt_pk_bf16_f32 v24, v36, v37
	v_cvt_pk_bf16_f32 v25, v38, v39
	v_cvt_pk_bf16_f32 v27, v30, v31
	global_store_dwordx4 v[28:29], v[24:27], off
	v_cvt_pk_bf16_f32 v8, v20, v21
	v_cvt_pk_bf16_f32 v9, v22, v23
	v_cvt_pk_bf16_f32 v11, v14, v15
	global_store_dwordx4 v[12:13], v[8:11], off
	v_cvt_pk_bf16_f32 v4, v4, v5
	v_cvt_pk_bf16_f32 v5, v6, v7
	v_cvt_pk_bf16_f32 v6, v0, v1
	v_cvt_pk_bf16_f32 v7, v2, v3
	global_store_dwordx4 v[12:13], v[4:7], off offset:256
	s_cbranch_vccz .LBB0_101
	s_setprio 0
	s_waitcnt vmcnt(0)
	v_readlane_b32 s44, v255, 6
	s_cmpk_gt_u32 s4, 0xff
	v_readlane_b32 s45, v255, 7
	s_cbranch_scc1 .LBB0_108
	s_barrier

; #define G_STAGE(bufoff, gbase, voff) do { _Pragma("unroll") for (int _i = 0; _i < 2; ++_i) \
;         __builtin_amdgcn_global_load_lds((const unsigned*)((const char*)(gbase) + (voff)[_i]), (LAS unsigned*)(lds + (bufoff) + ldsw + _i * 8192), 16, 0, 0); } while (0)
; #define G_LDA(dst, b, h) do { _Pragma("unroll") for (int m = 0; m < 4; ++m) _Pragma("unroll") for (int k = 0; k < 2; ++k) dst[m][k] = *(const LAS bf16x8*)(lds + G_SA(b, h) + aoff + m * 2048 + k * 1024); } while (0)
; #define G_LDB(dst, b, h) do { _Pragma("unroll") for (int n = 0; n < 2; ++n) _Pragma("unroll") for (int k = 0; k < 2; ++k) dst[n][k] = *(const LAS bf16x8*)(lds + G_SB(b, h) + boff + n * 2048 + k * 1024); } while (0)
; #define G_MMA(ai, bj, At, Bt) do { __builtin_amdgcn_s_setprio(1); _Pragma("unroll") for (int m = 0; m < 4; ++m) _Pragma("unroll") for (int n = 0; n < 2; ++n) _Pragma("unroll") for (int k = 0; k < 2; ++k) \
;         acc[ai][bj][m][n] = __builtin_amdgcn_mfma_f32_16x16x32_bf16(Bt[n][k], At[m][k], acc[ai][bj][m][n], 0, 0, 0); __builtin_amdgcn_s_setprio(0); } while (0)
; #define G_WAIT_V(n) asm volatile("s_waitcnt vmcnt(" #n ")" ::: "memory")
; #define G_WAIT_L(n) asm volatile("s_waitcnt lgkmcnt(" #n ")" ::: "memory")
; #define G_BAR __builtin_amdgcn_s_barrier()
; template <class J>
; DI void gemm_phase(LAS unsigned char* lds, const J& job) {
;     ...
;       const bool last = (t == nt - 2);
;       const char* a1 = cA + G_KT(t + 1);
;       const char* a2 = last ? nA + G_KT(0) : cA + G_KT(t + 2); const char* b2 = last ? nB + G_KT(0) : cB + G_KT(t + 2);
;       const char* a3 = last ? nA + G_KT(1) : cA + G_KT(t + 3); const char* b3 = last ? nB + G_KT(1) : cB + G_KT(t + 3);
;       G_LDB(B0, 0, 0); G_SCHED; G_LDA(At, 0, 0); G_STAGE(G_SA(1, 1), a1 + hstepA, voffA);
;       G_WAIT_L(8); G_BAR; G_WAIT_L(0); G_MMA(0, 0, At, B0); G_BAR; G_SCHED;
;       G_LDB(B1, 0, 1); G_STAGE(G_SB(0, 0), b2, voffB);
;       G_BAR; G_WAIT_L(0); G_MMA(0, 1, At, B1); G_BAR;
;       G_LDA(At, 0, 1); G_STAGE(G_SA(0, 0), a2, voffA);
;       G_BAR; G_WAIT_L(0); G_MMA(1, 0, At, B0); G_BAR; G_SCHED;
;       G_STAGE(G_SB(0, 1), b2 + hstepB, voffB);
;       G_WAIT_V(6); G_BAR; G_MMA(1, 1, At, B1); G_BAR;
;       G_LDB(B0, 1, 0); G_SCHED; G_LDA(At, 1, 0); G_STAGE(G_SA(0, 1), a2 + hstepA, voffA);
;       G_WAIT_L(8); G_BAR; G_WAIT_L(0); G_MMA(0, 0, At, B0); G_BAR; G_SCHED;
.LBB0_282:
	s_add_i32 s1, s56, 0xffffff80
	s_and_b32 s0, s7, 0xf80
	s_and_b32 s1, s1, 0xf00
	s_add_u32 s10, s68, s1
	s_addc_u32 s11, s69, 0
	s_add_u32 s1, s66, s1
	s_addc_u32 s57, s67, 0
	s_and_b32 s70, s56, 0xf80
	s_add_u32 s71, s68, s70
	s_addc_u32 s72, s69, 0
	s_add_u32 s70, s66, s70
	s_addc_u32 s80, s67, 0
	s_cmp_eq_u32 s6, 28
	s_cselect_b32 s75, s46, s11
	s_cselect_b32 s74, s21, s10
	s_cselect_b32 s77, s96, s57
	s_cselect_b32 s76, s47, s1
	s_cselect_b32 s73, s97, s72
	s_cselect_b32 s72, s33, s71
	s_cselect_b32 s71, vcc_hi, s80
	s_cselect_b32 s70, vcc_lo, s70
	s_add_i32 s1, s84, 0x100
	v_add_u32_e32 v142, s1, v150
	ds_read_b128 v[134:137], v142
	ds_read_b128 v[138:141], v142 offset:1024
	ds_read_b128 v[152:155], v142 offset:2048
	ds_read_b128 v[156:159], v142 offset:3072
	s_add_u32 s10, s9, s0
	s_addc_u32 s11, s19, 0
	v_lshl_add_u64 v[142:143], s[10:11], 0, v[128:129]
	s_add_i32 m0, s15, 0xc000
	ds_read_b128 v[160:163], v151
	ds_read_b128 v[164:167], v151 offset:1024
	ds_read_b128 v[168:171], v151 offset:2048
	ds_read_b128 v[172:175], v151 offset:3072
	ds_read_b128 v[176:179], v151 offset:4096
	ds_read_b128 v[180:183], v151 offset:5120
	ds_read_b128 v[184:187], v151 offset:6144
	ds_read_b128 v[188:191], v151 offset:7168
	global_load_lds_dwordx4 v[142:143], off
	s_add_i32 m0, s15, 0xe000
	v_lshl_add_u64 v[142:143], s[10:11], 0, v[130:131]
	global_load_lds_dwordx4 v[142:143], off
	s_waitcnt lgkmcnt(8)
	s_barrier
	s_waitcnt lgkmcnt(0)
	v_mfma_f32_16x16x32_bf16 v[124:127], v[134:137], v[160:163], v[124:127]
	v_mfma_f32_16x16x32_bf16 v[120:123], v[152:155], v[160:163], v[120:123]
	v_mfma_f32_16x16x32_bf16 v[108:111], v[134:137], v[168:171], v[108:111]
	v_mfma_f32_16x16x32_bf16 v[104:107], v[152:155], v[168:171], v[104:107]
	v_mfma_f32_16x16x32_bf16 v[92:95], v[134:137], v[176:179], v[92:95]
	v_mfma_f32_16x16x32_bf16 v[88:91], v[152:155], v[176:179], v[88:91]
	v_mfma_f32_16x16x32_bf16 v[76:79], v[134:137], v[184:187], v[76:79]
	v_mfma_f32_16x16x32_bf16 v[72:75], v[152:155], v[184:187], v[72:75]
	v_mfma_f32_16x16x32_bf16 v[124:127], v[138:141], v[164:167], v[124:127]
	v_mfma_f32_16x16x32_bf16 v[120:123], v[156:159], v[164:167], v[120:123]
	v_mfma_f32_16x16x32_bf16 v[108:111], v[138:141], v[172:175], v[108:111]
	v_mfma_f32_16x16x32_bf16 v[104:107], v[156:159], v[172:175], v[104:107]
	v_mfma_f32_16x16x32_bf16 v[92:95], v[138:141], v[180:183], v[92:95]
	v_mfma_f32_16x16x32_bf16 v[88:91], v[156:159], v[180:183], v[88:91]
	v_mfma_f32_16x16x32_bf16 v[76:79], v[138:141], v[188:191], v[76:79]
	v_mfma_f32_16x16x32_bf16 v[72:75], v[156:159], v[188:191], v[72:75]
	s_barrier
	s_add_i32 s0, s85, 0x100
	v_add_u32_e32 v142, s0, v150
	s_add_i32 s1, s1, s5
	ds_read_b128 v[192:195], v142
	ds_read_b128 v[196:199], v142 offset:1024
	ds_read_b128 v[200:203], v142 offset:2048
	ds_read_b128 v[204:207], v142 offset:3072
	s_mov_b32 m0, s1
	v_lshl_add_u64 v[142:143], s[76:77], 0, v[146:147]
	global_load_lds_dwordx4 v[142:143], off
	s_add_i32 m0, s1, 0x2000
	v_lshl_add_u64 v[142:143], s[76:77], 0, v[132:133]
	global_load_lds_dwordx4 v[142:143], off
	s_barrier
	s_waitcnt lgkmcnt(0)
	v_mfma_f32_16x16x32_bf16 v[116:119], v[192:195], v[160:163], v[116:119]
	v_mfma_f32_16x16x32_bf16 v[112:115], v[200:203], v[160:163], v[112:115]
	v_mfma_f32_16x16x32_bf16 v[100:103], v[192:195], v[168:171], v[100:103]
	v_mfma_f32_16x16x32_bf16 v[96:99], v[200:203], v[168:171], v[96:99]
	v_mfma_f32_16x16x32_bf16 v[84:87], v[192:195], v[176:179], v[84:87]
	v_mfma_f32_16x16x32_bf16 v[80:83], v[200:203], v[176:179], v[80:83]
	v_mfma_f32_16x16x32_bf16 v[68:71], v[192:195], v[184:187], v[68:71]
	v_mfma_f32_16x16x32_bf16 v[64:67], v[200:203], v[184:187], v[64:67]
	v_mfma_f32_16x16x32_bf16 v[116:119], v[196:199], v[164:167], v[116:119]
	v_mfma_f32_16x16x32_bf16 v[112:115], v[204:207], v[164:167], v[112:115]
	v_mfma_f32_16x16x32_bf16 v[100:103], v[196:199], v[172:175], v[100:103]
	v_mfma_f32_16x16x32_bf16 v[96:99], v[204:207], v[172:175], v[96:99]
	v_mfma_f32_16x16x32_bf16 v[84:87], v[196:199], v[180:183], v[84:87]
	v_mfma_f32_16x16x32_bf16 v[80:83], v[204:207], v[180:183], v[80:83]
	v_mfma_f32_16x16x32_bf16 v[68:71], v[196:199], v[188:191], v[68:71]
	v_mfma_f32_16x16x32_bf16 v[64:67], v[204:207], v[188:191], v[64:67]
	s_mov_b32 m0, s15
	v_lshl_add_u64 v[142:143], s[74:75], 0, v[128:129]
	s_barrier
	ds_read_b128 v[160:163], v151 offset:16384
	ds_read_b128 v[164:167], v151 offset:17408
	ds_read_b128 v[168:171], v151 offset:18432
	ds_read_b128 v[172:175], v151 offset:19456
	ds_read_b128 v[176:179], v151 offset:20480
	ds_read_b128 v[180:183], v151 offset:21504
	ds_read_b128 v[184:187], v151 offset:22528
	ds_read_b128 v[188:191], v151 offset:23552
	global_load_lds_dwordx4 v[142:143], off
	s_mov_b32 m0, s24
	v_lshl_add_u64 v[142:143], s[74:75], 0, v[130:131]
	global_load_lds_dwordx4 v[142:143], off
	s_barrier
	s_waitcnt lgkmcnt(0)
	v_mfma_f32_16x16x32_bf16 v[60:63], v[134:137], v[160:163], v[60:63]
	v_mfma_f32_16x16x32_bf16 v[56:59], v[152:155], v[160:163], v[56:59]
	v_mfma_f32_16x16x32_bf16 v[44:47], v[134:137], v[168:171], v[44:47]
	v_mfma_f32_16x16x32_bf16 v[40:43], v[152:155], v[168:171], v[40:43]
	v_mfma_f32_16x16x32_bf16 v[28:31], v[134:137], v[176:179], v[28:31]
	v_mfma_f32_16x16x32_bf16 v[24:27], v[152:155], v[176:179], v[24:27]
	v_mfma_f32_16x16x32_bf16 v[12:15], v[134:137], v[184:187], v[12:15]
	v_mfma_f32_16x16x32_bf16 v[8:11], v[152:155], v[184:187], v[8:11]
	v_mfma_f32_16x16x32_bf16 v[60:63], v[138:141], v[164:167], v[60:63]
	v_mfma_f32_16x16x32_bf16 v[56:59], v[156:159], v[164:167], v[56:59]
	v_mfma_f32_16x16x32_bf16 v[44:47], v[138:141], v[172:175], v[44:47]
	v_mfma_f32_16x16x32_bf16 v[40:43], v[156:159], v[172:175], v[40:43]
	v_mfma_f32_16x16x32_bf16 v[28:31], v[138:141], v[180:183], v[28:31]
	v_mfma_f32_16x16x32_bf16 v[24:27], v[156:159], v[180:183], v[24:27]
	v_mfma_f32_16x16x32_bf16 v[12:15], v[138:141], v[188:191], v[12:15]
	v_mfma_f32_16x16x32_bf16 v[8:11], v[156:159], v[188:191], v[8:11]
	s_barrier
; #define G_STAGE(bufoff, gbase, voff) do { _Pragma("unroll") for (int _i = 0; _i < 2; ++_i) \
;         __builtin_amdgcn_global_load_lds((const unsigned*)((const char*)(gbase) + (voff)[_i]), (LAS unsigned*)(lds + (bufoff) + ldsw + _i * 8192), 16, 0, 0); } while (0)
; #define G_LDA(dst, b, h) do { _Pragma("unroll") for (int m = 0; m < 4; ++m) _Pragma("unroll") for (int k = 0; k < 2; ++k) dst[m][k] = *(const LAS bf16x8*)(lds + G_SA(b, h) + aoff + m * 2048 + k * 1024); } while (0)
; #define G_LDB(dst, b, h) do { _Pragma("unroll") for (int n = 0; n < 2; ++n) _Pragma("unroll") for (int k = 0; k < 2; ++k) dst[n][k] = *(const LAS bf16x8*)(lds + G_SB(b, h) + boff + n * 2048 + k * 1024); } while (0)
; #define G_MMA(ai, bj, At, Bt) do { __builtin_amdgcn_s_setprio(1); _Pragma("unroll") for (int m = 0; m < 4; ++m) _Pragma("unroll") for (int n = 0; n < 2; ++n) _Pragma("unroll") for (int k = 0; k < 2; ++k) \
;         acc[ai][bj][m][n] = __builtin_amdgcn_mfma_f32_16x16x32_bf16(Bt[n][k], At[m][k], acc[ai][bj][m][n], 0, 0, 0); __builtin_amdgcn_s_setprio(0); } while (0)
; #define G_WAIT_V(n) asm volatile("s_waitcnt vmcnt(" #n ")" ::: "memory")
; #define G_WAIT_L(n) asm volatile("s_waitcnt lgkmcnt(" #n ")" ::: "memory")
; #define G_BAR __builtin_amdgcn_s_barrier()
; #define G_SCHED __builtin_amdgcn_sched_barrier(0)
; template <class J>
; DI void gemm_phase(LAS unsigned char* lds, const J& job) {
;     ...
;       G_STAGE(G_SB(0, 1), b2 + hstepB, voffB);
;       G_WAIT_V(6); G_BAR; G_MMA(1, 1, At, B1); G_BAR;
;       G_LDB(B0, 1, 0); G_SCHED; G_LDA(At, 1, 0); G_STAGE(G_SA(0, 1), a2 + hstepA, voffA);
;       G_WAIT_L(8); G_BAR; G_WAIT_L(0); G_MMA(0, 0, At, B0); G_BAR; G_SCHED;
;       G_LDB(B1, 1, 1); G_STAGE(G_SB(1, 0), b3, voffB);
;       G_BAR; G_WAIT_L(0); G_MMA(0, 1, At, B1); G_BAR;
;       G_LDA(At, 1, 1); G_STAGE(G_SA(1, 0), a3, voffA);
;       G_BAR; G_WAIT_L(0); G_MMA(1, 0, At, B0); G_BAR; G_SCHED;
	s_add_u32 s10, s76, 0x80000
	s_addc_u32 s11, s77, 0
	s_add_i32 s0, s0, s5
	s_mov_b32 m0, s0
	v_lshl_add_u64 v[134:135], s[10:11], 0, v[146:147]
	global_load_lds_dwordx4 v[134:135], off
	s_add_i32 m0, s0, 0x2000
	v_lshl_add_u64 v[134:135], s[10:11], 0, v[132:133]
	global_load_lds_dwordx4 v[134:135], off
	s_waitcnt vmcnt(6)
	s_barrier
	v_mfma_f32_16x16x32_bf16 v[52:55], v[192:195], v[160:163], v[52:55]
	v_mfma_f32_16x16x32_bf16 v[48:51], v[200:203], v[160:163], v[48:51]
	v_mfma_f32_16x16x32_bf16 v[36:39], v[192:195], v[168:171], v[36:39]
	v_mfma_f32_16x16x32_bf16 v[32:35], v[200:203], v[168:171], v[32:35]
	v_mfma_f32_16x16x32_bf16 v[20:23], v[192:195], v[176:179], v[20:23]
	v_mfma_f32_16x16x32_bf16 v[16:19], v[200:203], v[176:179], v[16:19]
	v_mfma_f32_16x16x32_bf16 v[4:7], v[192:195], v[184:187], v[4:7]
	v_mfma_f32_16x16x32_bf16 v[0:3], v[200:203], v[184:187], v[0:3]
	v_mfma_f32_16x16x32_bf16 v[52:55], v[196:199], v[164:167], v[52:55]
	v_mfma_f32_16x16x32_bf16 v[48:51], v[204:207], v[164:167], v[48:51]
	v_mfma_f32_16x16x32_bf16 v[36:39], v[196:199], v[172:175], v[36:39]
	v_mfma_f32_16x16x32_bf16 v[32:35], v[204:207], v[172:175], v[32:35]
	v_mfma_f32_16x16x32_bf16 v[20:23], v[196:199], v[180:183], v[20:23]
	v_mfma_f32_16x16x32_bf16 v[16:19], v[204:207], v[180:183], v[16:19]
	v_mfma_f32_16x16x32_bf16 v[4:7], v[196:199], v[188:191], v[4:7]
	v_mfma_f32_16x16x32_bf16 v[0:3], v[204:207], v[188:191], v[0:3]
	s_add_i32 s0, s88, 0x100
	v_add_u32_e32 v142, s0, v150
	s_barrier
	ds_read_b128 v[134:137], v142
	ds_read_b128 v[138:141], v142 offset:1024
	ds_read_b128 v[152:155], v142 offset:2048
	ds_read_b128 v[156:159], v142 offset:3072
	s_add_u32 s10, s74, 0x80000
	s_addc_u32 s11, s75, 0
	s_mov_b32 m0, s25
	v_lshl_add_u64 v[142:143], s[10:11], 0, v[128:129]
	ds_read_b128 v[160:163], v151 offset:32768
	ds_read_b128 v[164:167], v151 offset:33792
	ds_read_b128 v[168:171], v151 offset:34816
	ds_read_b128 v[172:175], v151 offset:35840
	ds_read_b128 v[176:179], v151 offset:36864
	ds_read_b128 v[180:183], v151 offset:37888
	ds_read_b128 v[184:187], v151 offset:38912
	ds_read_b128 v[188:191], v151 offset:39936
	global_load_lds_dwordx4 v[142:143], off
	s_mov_b32 m0, s36
	v_lshl_add_u64 v[142:143], s[10:11], 0, v[130:131]
	global_load_lds_dwordx4 v[142:143], off
	s_waitcnt lgkmcnt(8)
	s_barrier
	s_waitcnt lgkmcnt(0)
	v_mfma_f32_16x16x32_bf16 v[124:127], v[134:137], v[160:163], v[124:127]
	v_mfma_f32_16x16x32_bf16 v[120:123], v[152:155], v[160:163], v[120:123]
	v_mfma_f32_16x16x32_bf16 v[108:111], v[134:137], v[168:171], v[108:111]
	v_mfma_f32_16x16x32_bf16 v[104:107], v[152:155], v[168:171], v[104:107]
	v_mfma_f32_16x16x32_bf16 v[92:95], v[134:137], v[176:179], v[92:95]
	v_mfma_f32_16x16x32_bf16 v[88:91], v[152:155], v[176:179], v[88:91]
	v_mfma_f32_16x16x32_bf16 v[76:79], v[134:137], v[184:187], v[76:79]
	v_mfma_f32_16x16x32_bf16 v[72:75], v[152:155], v[184:187], v[72:75]
	v_mfma_f32_16x16x32_bf16 v[124:127], v[138:141], v[164:167], v[124:127]
	v_mfma_f32_16x16x32_bf16 v[120:123], v[156:159], v[164:167], v[120:123]
	v_mfma_f32_16x16x32_bf16 v[108:111], v[138:141], v[172:175], v[108:111]
	v_mfma_f32_16x16x32_bf16 v[104:107], v[156:159], v[172:175], v[104:107]
	v_mfma_f32_16x16x32_bf16 v[92:95], v[138:141], v[180:183], v[92:95]
	v_mfma_f32_16x16x32_bf16 v[88:91], v[156:159], v[180:183], v[88:91]
	v_mfma_f32_16x16x32_bf16 v[76:79], v[138:141], v[188:191], v[76:79]
	v_mfma_f32_16x16x32_bf16 v[72:75], v[156:159], v[188:191], v[72:75]
	s_barrier
	s_add_i32 s1, s89, 0x100
	v_add_u32_e32 v142, s1, v150
	s_add_i32 s0, s0, s5
	ds_read_b128 v[192:195], v142
	ds_read_b128 v[196:199], v142 offset:1024
	ds_read_b128 v[200:203], v142 offset:2048
	ds_read_b128 v[204:207], v142 offset:3072
	s_mov_b32 m0, s0
	v_lshl_add_u64 v[142:143], s[70:71], 0, v[146:147]
	global_load_lds_dwordx4 v[142:143], off
	s_add_i32 m0, s0, 0x2000
	v_lshl_add_u64 v[142:143], s[70:71], 0, v[132:133]
	global_load_lds_dwordx4 v[142:143], off
	s_barrier
	s_waitcnt lgkmcnt(0)
	v_mfma_f32_16x16x32_bf16 v[116:119], v[192:195], v[160:163], v[116:119]
	v_mfma_f32_16x16x32_bf16 v[112:115], v[200:203], v[160:163], v[112:115]
	v_mfma_f32_16x16x32_bf16 v[100:103], v[192:195], v[168:171], v[100:103]
	v_mfma_f32_16x16x32_bf16 v[96:99], v[200:203], v[168:171], v[96:99]
	v_mfma_f32_16x16x32_bf16 v[84:87], v[192:195], v[176:179], v[84:87]
	v_mfma_f32_16x16x32_bf16 v[80:83], v[200:203], v[176:179], v[80:83]
	v_mfma_f32_16x16x32_bf16 v[68:71], v[192:195], v[184:187], v[68:71]
	v_mfma_f32_16x16x32_bf16 v[64:67], v[200:203], v[184:187], v[64:67]
	v_mfma_f32_16x16x32_bf16 v[116:119], v[196:199], v[164:167], v[116:119]
	v_mfma_f32_16x16x32_bf16 v[112:115], v[204:207], v[164:167], v[112:115]
	v_mfma_f32_16x16x32_bf16 v[100:103], v[196:199], v[172:175], v[100:103]
	v_mfma_f32_16x16x32_bf16 v[96:99], v[204:207], v[172:175], v[96:99]
	v_mfma_f32_16x16x32_bf16 v[84:87], v[196:199], v[180:183], v[84:87]
	v_mfma_f32_16x16x32_bf16 v[80:83], v[204:207], v[180:183], v[80:83]
	v_mfma_f32_16x16x32_bf16 v[68:71], v[196:199], v[188:191], v[68:71]
	v_mfma_f32_16x16x32_bf16 v[64:67], v[204:207], v[188:191], v[64:67]
	s_mov_b32 m0, s45
	v_lshl_add_u64 v[142:143], s[72:73], 0, v[128:129]
	s_barrier
; DI unsigned pk2(float lo, float hi) { unsigned r; asm("v_cvt_pk_bf16_f32 %0, %1, %2" : "=v"(r) : "v"(lo), "v"(hi)); return r; }
; #define G_STAGE(bufoff, gbase, voff) do { _Pragma("unroll") for (int _i = 0; _i < 2; ++_i) \
;         __builtin_amdgcn_global_load_lds((const unsigned*)((const char*)(gbase) + (voff)[_i]), (LAS unsigned*)(lds + (bufoff) + ldsw + _i * 8192), 16, 0, 0); } while (0)
; #define G_LDA(dst, b, h) do { _Pragma("unroll") for (int m = 0; m < 4; ++m) _Pragma("unroll") for (int k = 0; k < 2; ++k) dst[m][k] = *(const LAS bf16x8*)(lds + G_SA(b, h) + aoff + m * 2048 + k * 1024); } while (0)
; #define G_MMA(ai, bj, At, Bt) do { __builtin_amdgcn_s_setprio(1); _Pragma("unroll") for (int m = 0; m < 4; ++m) _Pragma("unroll") for (int n = 0; n < 2; ++n) _Pragma("unroll") for (int k = 0; k < 2; ++k) \
;         acc[ai][bj][m][n] = __builtin_amdgcn_mfma_f32_16x16x32_bf16(Bt[n][k], At[m][k], acc[ai][bj][m][n], 0, 0, 0); __builtin_amdgcn_s_setprio(0); } while (0)
; #define G_WAIT_V(n) asm volatile("s_waitcnt vmcnt(" #n ")" ::: "memory")
; #define G_WAIT_L(n) asm volatile("s_waitcnt lgkmcnt(" #n ")" ::: "memory")
; #define G_BAR __builtin_amdgcn_s_barrier()
; #define G_SCHED __builtin_amdgcn_sched_barrier(0)
; template <class J>
; DI void gemm_phase(LAS unsigned char* lds, const J& job) {
;     ...
;       G_LDA(At, 1, 1); G_STAGE(G_SA(1, 0), a3, voffA);
;       G_BAR; G_WAIT_L(0); G_MMA(1, 0, At, B0); G_BAR; G_SCHED;
;       G_STAGE(G_SB(1, 1), b3 + hstepB, voffB);
;       G_WAIT_V(6); G_BAR; G_MMA(1, 1, At, B1); G_BAR;
;   DI void epi(const Acc& acc, const Unit& u, int wr, int wc, int fr, int fq) const {
;     ...
;         const int rl = ai * HALF + wr * 64 + m * 16 + fr;
; #pragma unroll
;         for (int bj = 0; bj < 2; ++bj) {
;           const int col = u.pn * 256 + bj * HALF + wc * 32 + 8 * fq;
;           const f32x4 v0 = acc[ai][bj][m][0], v1 = acc[ai][bj][m][1];
;           const int row = u.pm * 256 + rl;
;           u32x4 o; o.x = pk2(v0.x, v0.y); o.y = pk2(v0.z, v0.w); o.z = pk2(v1.x, v1.y); o.w = pk2(v1.z, v1.w);
;           *(u32x4*)(proj + (size_t)row * NPROJ + col) = o;
;           if (u.pn >= 8 && u.pn < 12) {
;             const int isv = u.pn >= 10; const int cc = col - (isv ? C_BV : C_BK);
;             float* dst = out + (isv ? O_VP : O_KP) + ((size_t)l * TP + row) * 512 + cc;
;             *(f32x4*)dst = v0; *(f32x4*)(dst + 4) = v1;
	ds_read_b128 v[160:163], v151 offset:49152
	ds_read_b128 v[164:167], v151 offset:50176
	ds_read_b128 v[168:171], v151 offset:51200
	ds_read_b128 v[172:175], v151 offset:52224
	ds_read_b128 v[176:179], v151 offset:53248
	ds_read_b128 v[180:183], v151 offset:54272
	ds_read_b128 v[184:187], v151 offset:55296
	ds_read_b128 v[188:191], v151 offset:56320
	global_load_lds_dwordx4 v[142:143], off
	s_mov_b32 m0, s65
	v_lshl_add_u64 v[142:143], s[72:73], 0, v[130:131]
	global_load_lds_dwordx4 v[142:143], off
	s_barrier
	s_waitcnt lgkmcnt(0)
	v_mfma_f32_16x16x32_bf16 v[60:63], v[134:137], v[160:163], v[60:63]
	v_mfma_f32_16x16x32_bf16 v[56:59], v[152:155], v[160:163], v[56:59]
	v_mfma_f32_16x16x32_bf16 v[44:47], v[134:137], v[168:171], v[44:47]
	v_mfma_f32_16x16x32_bf16 v[40:43], v[152:155], v[168:171], v[40:43]
	v_mfma_f32_16x16x32_bf16 v[28:31], v[134:137], v[176:179], v[28:31]
	v_mfma_f32_16x16x32_bf16 v[24:27], v[152:155], v[176:179], v[24:27]
	v_mfma_f32_16x16x32_bf16 v[12:15], v[134:137], v[184:187], v[12:15]
	v_mfma_f32_16x16x32_bf16 v[8:11], v[152:155], v[184:187], v[8:11]
	v_mfma_f32_16x16x32_bf16 v[60:63], v[138:141], v[164:167], v[60:63]
	v_mfma_f32_16x16x32_bf16 v[56:59], v[156:159], v[164:167], v[56:59]
	v_mfma_f32_16x16x32_bf16 v[44:47], v[138:141], v[172:175], v[44:47]
	v_mfma_f32_16x16x32_bf16 v[40:43], v[156:159], v[172:175], v[40:43]
	v_mfma_f32_16x16x32_bf16 v[28:31], v[138:141], v[180:183], v[28:31]
	v_mfma_f32_16x16x32_bf16 v[24:27], v[156:159], v[180:183], v[24:27]
	v_mfma_f32_16x16x32_bf16 v[12:15], v[138:141], v[188:191], v[12:15]
	v_mfma_f32_16x16x32_bf16 v[8:11], v[156:159], v[188:191], v[8:11]
	s_barrier
	s_add_u32 s10, s70, 0x80000
	s_addc_u32 s11, s71, 0
	s_add_i32 s0, s1, s5
	s_mov_b32 m0, s0
	v_lshl_add_u64 v[134:135], s[10:11], 0, v[146:147]
	global_load_lds_dwordx4 v[134:135], off
	s_add_i32 m0, s0, 0x2000
	v_lshl_add_u64 v[134:135], s[10:11], 0, v[132:133]
	global_load_lds_dwordx4 v[134:135], off
	s_waitcnt vmcnt(6)
	s_barrier
	v_mfma_f32_16x16x32_bf16 v[52:55], v[192:195], v[160:163], v[52:55]
	v_mfma_f32_16x16x32_bf16 v[48:51], v[200:203], v[160:163], v[48:51]
	v_mfma_f32_16x16x32_bf16 v[36:39], v[192:195], v[168:171], v[36:39]
	v_mfma_f32_16x16x32_bf16 v[32:35], v[200:203], v[168:171], v[32:35]
	v_mfma_f32_16x16x32_bf16 v[20:23], v[192:195], v[176:179], v[20:23]
	v_mfma_f32_16x16x32_bf16 v[16:19], v[200:203], v[176:179], v[16:19]
	v_mfma_f32_16x16x32_bf16 v[4:7], v[192:195], v[184:187], v[4:7]
	v_mfma_f32_16x16x32_bf16 v[0:3], v[200:203], v[184:187], v[0:3]
	v_mfma_f32_16x16x32_bf16 v[52:55], v[196:199], v[164:167], v[52:55]
	v_mfma_f32_16x16x32_bf16 v[48:51], v[204:207], v[164:167], v[48:51]
	v_mfma_f32_16x16x32_bf16 v[36:39], v[196:199], v[172:175], v[36:39]
	v_mfma_f32_16x16x32_bf16 v[32:35], v[204:207], v[172:175], v[32:35]
	v_mfma_f32_16x16x32_bf16 v[20:23], v[196:199], v[180:183], v[20:23]
	v_mfma_f32_16x16x32_bf16 v[16:19], v[204:207], v[180:183], v[16:19]
	v_mfma_f32_16x16x32_bf16 v[4:7], v[196:199], v[188:191], v[4:7]
	v_mfma_f32_16x16x32_bf16 v[0:3], v[204:207], v[188:191], v[0:3]
	s_add_i32 s6, s6, 2
	s_addk_i32 s56, 0x100
	s_addk_i32 s7, 0x100
	s_cmp_gt_u32 s6, 29
	s_barrier
	s_cbranch_scc0 .LBB0_282
	v_mov_b32_e32 v135, v148
	v_mov_b32_e32 v134, v149
	s_lshl_b32 s0, s64, 8
	s_or_b32 s0, s0, s38
	v_lshl_add_u32 v134, v134, 3, s0
	s_lshl_b32 s0, s8, 8
	s_add_i32 s0, s0, s37
	v_add_u32_e32 v136, s0, v135
	s_and_b32 s0, s64, -4
	s_cmp_eq_u32 s0, 8
	s_cselect_b64 s[66:67], -1, 0
	s_cmp_gt_u32 s64, 9
	s_cselect_b64 s[6:7], -1, 0
	s_and_b64 s[6:7], s[6:7], exec
	s_movk_i32 s1, 0xf600
	v_mov_b64_e32 v[138:139], s[26:27]
	s_cselect_b32 s7, s1, 0xfffff800
	s_mov_b32 s1, 0x3040000
	v_ashrrev_i32_e32 v137, 31, v136
	v_mad_i64_i32 v[138:139], s[8:9], v136, s92, v[138:139]
	v_ashrrev_i32_e32 v135, 31, v134
	s_cselect_b32 s6, s1, 0x2040000
	s_cmp_lg_u32 s0, 8
	v_lshlrev_b64 v[140:141], 11, v[136:137]
	v_lshl_add_u64 v[142:143], v[134:135], 1, v[138:139]
	v_add_u32_e32 v138, s7, v134
	v_cvt_pk_bf16_f32 v152, v124, v125
	v_cvt_pk_bf16_f32 v153, v126, v127
	v_cvt_pk_bf16_f32 v154, v120, v121
	v_cvt_pk_bf16_f32 v155, v122, v123
	global_store_dwordx4 v[142:143], v[152:155], off
	s_cbranch_scc1 .LBB0_285
	s_lshl_b32 s0, s6, 2
	s_add_u32 s8, s83, s0
	s_addc_u32 s9, s86, 0
	v_lshl_add_u64 v[152:153], s[8:9], 0, v[140:141]
	v_ashrrev_i32_e32 v139, 31, v138
	v_lshl_add_u64 v[152:153], v[138:139], 2, v[152:153]
	global_store_dwordx4 v[152:153], v[124:127], off
	global_store_dwordx4 v[152:153], v[120:123], off offset:16
